# 128x128 GEMM loops: second K-step fragment reads issued early into spare registers
# baseline (speedup 1.0000x reference)
.LBB0_1406:
	s_cmp_lt_u32 s26, 10
	s_cselect_b32 s0, s41, s43
	v_mov_b32_e32 v79, s0
	s_movk_i32 s0, 0x180
	s_cselect_b32 s0, s0, 0x500
	v_mad_i64_i32 v[80:81], s[30:31], s0, v64, 0
	s_cselect_b32 s29, s40, s42
	s_cselect_b32 s30, 0, 0xfffffe80
	v_mov_b32_e32 v78, s29
	s_cselect_b32 s29, 0, -1
	s_add_u32 s30, s10, s30
	v_lshl_add_u64 v[78:79], v[80:81], 1, v[78:79]
	s_addc_u32 s31, s11, s29
	v_lshl_add_u64 v[78:79], s[30:31], 1, v[78:79]
	s_lshl_b32 s29, s28, 14
	s_waitcnt vmcnt(0)
	v_lshl_add_u64 v[82:83], v[78:79], 0, v[68:69]
	s_add_i32 s29, s14, s29
	s_lshl_b32 s0, s0, 5
	s_waitcnt lgkmcnt(0)
	s_barrier
	v_lshl_add_u64 v[78:79], v[82:83], 0, s[4:5]
	s_mov_b32 m0, s29
	v_lshl_add_u64 v[120:121], v[82:83], 0, s[0:1]
	global_load_lds_dwordx4 v[78:79], off
	v_lshl_add_u64 v[78:79], v[120:121], 0, s[4:5]
	s_add_i32 m0, s29, 0x400
	v_lshl_add_u64 v[122:123], v[66:67], 0, s[12:13]
	global_load_lds_dwordx4 v[78:79], off
	s_add_i32 m0, s29, 0x2000
	v_lshl_add_u64 v[78:79], v[122:123], 0, s[4:5]
	s_lshl_b32 s0, s27, 14
	global_load_lds_dwordx4 v[78:79], off
	s_add_i32 m0, s29, 0x2400
	v_add_u32_e32 v65, s0, v88
	v_or_b32_e32 v124, s0, v89
	s_add_i32 s0, s27, 1
	s_cmp_lg_u32 s27, 3
	s_mov_b64 s[30:31], 0x8080
	s_cselect_b32 s27, s0, 0
	s_add_i32 s0, s28, 1
	v_lshl_add_u64 v[78:79], v[122:123], 0, s[30:31]
	s_cmp_lg_u32 s28, 3
	global_load_lds_dwordx4 v[78:79], off
	s_cselect_b32 s0, s0, 0
	ds_read_b128 v[78:81], v65
	ds_read_b128 v[92:95], v65 offset:1024
	ds_read_b128 v[96:99], v65 offset:2048
	ds_read_b128 v[100:103], v65 offset:3072
	ds_read_b128 v[104:107], v124
	ds_read_b128 v[108:111], v124 offset:1024
	ds_read_b128 v[112:115], v124 offset:2048
	ds_read_b128 v[116:119], v124 offset:3072
	s_lshl_b32 s98, s27, 14
	v_add_u32_e32 v160, s98, v88
	v_or_b32_e32 v161, s98, v89
	ds_read_b128 v[128:131], v160
	ds_read_b128 v[132:135], v160 offset:1024
	ds_read_b128 v[136:139], v160 offset:2048
	ds_read_b128 v[140:143], v160 offset:3072
	ds_read_b128 v[144:147], v161
	ds_read_b128 v[148:151], v161 offset:1024
	ds_read_b128 v[152:155], v161 offset:2048
	ds_read_b128 v[156:159], v161 offset:3072
	s_waitcnt lgkmcnt(8)
	s_lshl_b32 s28, s0, 14
	s_add_i32 s30, s14, s28
	v_mfma_f32_16x16x32_bf16 v[60:63], v[104:107], v[78:81], v[60:63]
	v_mfma_f32_16x16x32_bf16 v[56:59], v[108:111], v[78:81], v[56:59]
	s_mov_b32 m0, s30
	s_mov_b64 s[28:29], 0x80c0
	s_add_i32 s26, s26, 2
	v_mfma_f32_16x16x32_bf16 v[52:55], v[112:115], v[78:81], v[52:55]
	v_mfma_f32_16x16x32_bf16 v[48:51], v[116:119], v[78:81], v[48:51]
	v_lshl_add_u64 v[78:79], v[82:83], 0, s[6:7]
	global_load_lds_dwordx4 v[78:79], off
	v_lshl_add_u64 v[78:79], v[120:121], 0, s[6:7]
	s_add_i32 m0, s30, 0x400
	v_mfma_f32_16x16x32_bf16 v[44:47], v[104:107], v[92:95], v[44:47]
	global_load_lds_dwordx4 v[78:79], off
	s_add_i32 m0, s30, 0x2000
	v_lshl_add_u64 v[78:79], v[122:123], 0, s[6:7]
	global_load_lds_dwordx4 v[78:79], off
	v_lshl_add_u64 v[78:79], v[122:123], 0, s[28:29]
	s_add_i32 m0, s30, 0x2400
	s_lshl_b32 s28, s27, 14
	global_load_lds_dwordx4 v[78:79], off
	v_add_u32_e32 v65, s28, v88
	v_or_b32_e32 v82, s28, v89
	s_add_i32 s28, s27, 1
	v_mfma_f32_16x16x32_bf16 v[40:43], v[108:111], v[92:95], v[40:43]
	s_cmp_lg_u32 s27, 3
	s_cselect_b32 s27, s28, 0
	s_add_i32 s28, s0, 1
	v_mfma_f32_16x16x32_bf16 v[36:39], v[112:115], v[92:95], v[36:39]
	s_cmp_lg_u32 s0, 3
	s_cselect_b32 s28, s28, 0
	s_add_u32 s12, s12, 0x80
	v_mfma_f32_16x16x32_bf16 v[32:35], v[116:119], v[92:95], v[32:35]
	s_addc_u32 s13, s13, 0
	s_add_u32 s10, s10, 64
	s_addc_u32 s11, s11, 0
	v_mfma_f32_16x16x32_bf16 v[28:31], v[104:107], v[96:99], v[28:31]
	s_cmpk_eq_i32 s12, 0x780
	v_mfma_f32_16x16x32_bf16 v[24:27], v[108:111], v[96:99], v[24:27]
	v_mfma_f32_16x16x32_bf16 v[20:23], v[112:115], v[96:99], v[20:23]
	v_mfma_f32_16x16x32_bf16 v[16:19], v[116:119], v[96:99], v[16:19]
	v_mfma_f32_16x16x32_bf16 v[12:15], v[104:107], v[100:103], v[12:15]
	v_mfma_f32_16x16x32_bf16 v[8:11], v[108:111], v[100:103], v[8:11]
	v_mfma_f32_16x16x32_bf16 v[4:7], v[112:115], v[100:103], v[4:7]
	v_mfma_f32_16x16x32_bf16 v[0:3], v[116:119], v[100:103], v[0:3]
	s_waitcnt lgkmcnt(0)
	s_nop 0
	v_mfma_f32_16x16x32_bf16 v[60:63], v[144:147], v[128:131], v[60:63]
	v_mfma_f32_16x16x32_bf16 v[56:59], v[148:151], v[128:131], v[56:59]
	v_mfma_f32_16x16x32_bf16 v[52:55], v[152:155], v[128:131], v[52:55]
	v_mfma_f32_16x16x32_bf16 v[48:51], v[156:159], v[128:131], v[48:51]
	v_mfma_f32_16x16x32_bf16 v[44:47], v[144:147], v[132:135], v[44:47]
	v_mfma_f32_16x16x32_bf16 v[40:43], v[148:151], v[132:135], v[40:43]
	v_mfma_f32_16x16x32_bf16 v[36:39], v[152:155], v[132:135], v[36:39]
	v_mfma_f32_16x16x32_bf16 v[32:35], v[156:159], v[132:135], v[32:35]
	v_mfma_f32_16x16x32_bf16 v[28:31], v[144:147], v[136:139], v[28:31]
	v_mfma_f32_16x16x32_bf16 v[24:27], v[148:151], v[136:139], v[24:27]
	v_mfma_f32_16x16x32_bf16 v[20:23], v[152:155], v[136:139], v[20:23]
	v_mfma_f32_16x16x32_bf16 v[16:19], v[156:159], v[136:139], v[16:19]
	v_mfma_f32_16x16x32_bf16 v[12:15], v[144:147], v[140:143], v[12:15]
	v_mfma_f32_16x16x32_bf16 v[8:11], v[148:151], v[140:143], v[8:11]
	v_mfma_f32_16x16x32_bf16 v[4:7], v[152:155], v[140:143], v[4:7]
	v_mfma_f32_16x16x32_bf16 v[0:3], v[156:159], v[140:143], v[0:3]
	s_cbranch_scc0 .LBB0_1406
	s_waitcnt vmcnt(4)
	s_waitcnt lgkmcnt(0)
	s_barrier
	ds_read_b128 v[64:67], v88 offset:32768
	ds_read_b128 v[78:81], v88 offset:33792
	ds_read_b128 v[92:95], v88 offset:34816
	ds_read_b128 v[96:99], v88 offset:35840
	ds_read_b128 v[100:103], v89 offset:32768
	ds_read_b128 v[104:107], v89 offset:33792
	ds_read_b128 v[108:111], v89 offset:34816
	ds_read_b128 v[112:115], v89 offset:35840
	s_waitcnt lgkmcnt(0)
	s_waitcnt vmcnt(0)
	s_waitcnt lgkmcnt(0)
	s_barrier
	v_mfma_f32_16x16x32_bf16 v[56:59], v[104:107], v[64:67], v[56:59]
	s_movk_i32 s0, 0xfff
	v_readlane_b32 s36, v241, 1
	v_mfma_f32_16x16x32_bf16 v[40:43], v[104:107], v[78:81], v[40:43]
	v_readlane_b32 s44, v241, 9
	v_readlane_b32 s45, v241, 10
	s_add_i32 s2, s2, s3
	v_mfma_f32_16x16x32_bf16 v[24:27], v[104:107], v[92:95], v[24:27]
	s_add_i32 s15, s15, s16
	s_cmpk_gt_i32 s2, 0x9f
	v_readlane_b32 s37, v241, 2
	v_mfma_f32_16x16x32_bf16 v[52:55], v[108:111], v[64:67], v[52:55]
	v_readlane_b32 s38, v241, 3
	v_readlane_b32 s39, v241, 4
	v_readlane_b32 s40, v241, 5
	v_mfma_f32_16x16x32_bf16 v[36:39], v[108:111], v[78:81], v[36:39]
	v_readlane_b32 s41, v241, 6
	v_readlane_b32 s42, v241, 7
	v_readlane_b32 s43, v241, 8
	v_mfma_f32_16x16x32_bf16 v[20:23], v[108:111], v[92:95], v[20:23]
	v_readlane_b32 s46, v241, 11
	v_readlane_b32 s47, v241, 12
	v_readlane_b32 s48, v241, 13
	v_mfma_f32_16x16x32_bf16 v[60:63], v[100:103], v[64:67], v[60:63]
	v_readlane_b32 s49, v241, 14
	v_readlane_b32 s50, v241, 15
	v_readlane_b32 s51, v241, 16
	v_mfma_f32_16x16x32_bf16 v[48:51], v[112:115], v[64:67], v[48:51]
	v_mfma_f32_16x16x32_bf16 v[44:47], v[100:103], v[78:81], v[44:47]
	v_mfma_f32_16x16x32_bf16 v[32:35], v[112:115], v[78:81], v[32:35]
	v_mfma_f32_16x16x32_bf16 v[28:31], v[100:103], v[92:95], v[28:31]
	v_mfma_f32_16x16x32_bf16 v[16:19], v[112:115], v[92:95], v[16:19]
	v_mfma_f32_16x16x32_bf16 v[12:15], v[100:103], v[96:99], v[12:15]
	v_mfma_f32_16x16x32_bf16 v[8:11], v[104:107], v[96:99], v[8:11]
	v_mfma_f32_16x16x32_bf16 v[4:7], v[108:111], v[96:99], v[4:7]
	v_mfma_f32_16x16x32_bf16 v[0:3], v[112:115], v[96:99], v[0:3]
	ds_read_b128 v[64:67], v88 offset:49152
	ds_read_b128 v[78:81], v88 offset:50176
	ds_read_b128 v[92:95], v88 offset:51200
	ds_read_b128 v[96:99], v88 offset:52224
	ds_read_b128 v[100:103], v89 offset:49152
	ds_read_b128 v[104:107], v89 offset:50176
	ds_read_b128 v[108:111], v89 offset:51200
	ds_read_b128 v[112:115], v89 offset:52224
	s_waitcnt lgkmcnt(0)
	s_waitcnt lgkmcnt(0)
	s_barrier
	v_mfma_f32_16x16x32_bf16 v[120:123], v[104:107], v[64:67], v[56:59]
	v_mfma_f32_16x16x32_bf16 v[56:59], v[104:107], v[78:81], v[40:43]
	v_mfma_f32_16x16x32_bf16 v[40:43], v[104:107], v[92:95], v[24:27]
	s_nop 2
	v_add_u32_e32 v24, s24, v86
	v_mfma_f32_16x16x32_bf16 v[124:127], v[108:111], v[64:67], v[52:55]
	v_cmp_lt_i32_e32 vcc, s0, v24
	s_movk_i32 s0, 0x6000
	v_mfma_f32_16x16x32_bf16 v[52:55], v[108:111], v[78:81], v[36:39]
	v_mfma_f32_16x16x32_bf16 v[36:39], v[108:111], v[92:95], v[20:23]
	s_nop 2
	v_add_u32_e32 v21, 0xfffff000, v24
	v_lshrrev_b32_e32 v21, 12, v21
	v_add_u32_e32 v21, 1, v21
	v_or_b32_e32 v20, s25, v87
	v_cndmask_b32_e32 v21, 0, v21, vcc
	v_mad_u64_u32 v[22:23], s[10:11], v21, s0, v[74:75]
	v_ashrrev_i32_e32 v21, 31, v20
	v_mfma_f32_16x16x32_bf16 v[116:119], v[100:103], v[64:67], v[60:63]
	s_mov_b64 s[10:11], 0x2000
	s_movk_i32 s0, 0x2000
	v_mfma_f32_16x16x32_bf16 v[64:67], v[112:115], v[64:67], v[48:51]
	v_mfma_f32_16x16x32_bf16 v[60:63], v[100:103], v[78:81], v[44:47]
	v_mfma_f32_16x16x32_bf16 v[48:51], v[112:115], v[78:81], v[32:35]
	v_lshlrev_b64 v[78:79], 2, v[20:21]
	v_lshl_add_u64 v[20:21], v[22:23], 0, v[78:79]
	v_lshl_add_u64 v[20:21], v[20:21], 0, v[76:77]
	v_lshl_add_u64 v[22:23], v[20:21], 0, s[10:11]
	v_add_co_u32_e32 v20, vcc, s0, v20
	v_mfma_f32_16x16x32_bf16 v[44:47], v[100:103], v[92:95], v[28:31]
	s_nop 0
	v_addc_co_u32_e32 v21, vcc, 0, v21, vcc
	v_mfma_f32_16x16x32_bf16 v[16:19], v[112:115], v[92:95], v[16:19]
	v_or_b32_e32 v92, v24, v84
	v_or_b32_e32 v82, 32, v92
	v_or_b32_e32 v80, 48, v92
	v_mfma_f32_16x16x32_bf16 v[12:15], v[100:103], v[96:99], v[12:15]
	global_load_dwordx4 v[32:35], v[20:21], off
	global_load_dwordx4 v[28:31], v[22:23], off offset:64
	global_load_dwordx4 v[24:27], v[22:23], off offset:128
	s_nop 0
	global_load_dwordx4 v[20:23], v[22:23], off offset:192
	v_mfma_f32_16x16x32_bf16 v[8:11], v[104:107], v[96:99], v[8:11]
	v_mfma_f32_16x16x32_bf16 v[4:7], v[108:111], v[96:99], v[4:7]
	v_mfma_f32_16x16x32_bf16 v[0:3], v[112:115], v[96:99], v[0:3]
	v_or_b32_e32 v96, 16, v92
	s_nop 0
	v_ashrrev_i32_e32 v93, 31, v92
	v_lshlrev_b64 v[92:93], 12, v[92:93]
	v_lshl_add_u64 v[92:93], s[44:45], 0, v[92:93]
	v_lshl_add_u64 v[92:93], v[92:93], 0, v[78:79]
	v_lshl_add_u64 v[98:99], v[92:93], 0, v[76:77]
	global_load_dwordx4 v[92:95], v[98:99], off
	s_waitcnt vmcnt(0)
	v_pk_mul_f32 v[92:93], v[92:93], s[8:9] op_sel_hi:[1,0]
	v_pk_mul_f32 v[94:95], v[94:95], s[8:9] op_sel_hi:[1,0]
	v_pk_fma_f32 v[92:93], v[116:117], v[32:33], v[92:93]
	v_pk_fma_f32 v[94:95], v[118:119], v[34:35], v[94:95]
	global_store_dwordx4 v[98:99], v[92:95], off
	global_load_dwordx4 v[92:95], v[98:99], off offset:64
	s_waitcnt vmcnt(0)
	v_pk_mul_f32 v[92:93], v[92:93], s[8:9] op_sel_hi:[1,0]
	v_pk_mul_f32 v[94:95], v[94:95], s[8:9] op_sel_hi:[1,0]
	v_pk_fma_f32 v[92:93], v[120:121], v[28:29], v[92:93]
	v_pk_fma_f32 v[94:95], v[122:123], v[30:31], v[94:95]
	global_store_dwordx4 v[98:99], v[92:95], off offset:64
	global_load_dwordx4 v[92:95], v[98:99], off offset:128
	s_waitcnt vmcnt(0)
	v_pk_mul_f32 v[92:93], v[92:93], s[8:9] op_sel_hi:[1,0]
	v_pk_mul_f32 v[94:95], v[94:95], s[8:9] op_sel_hi:[1,0]
	v_pk_fma_f32 v[92:93], v[124:125], v[24:25], v[92:93]
	v_pk_fma_f32 v[94:95], v[126:127], v[26:27], v[94:95]
	global_store_dwordx4 v[98:99], v[92:95], off offset:128
	global_load_dwordx4 v[92:95], v[98:99], off offset:192
	s_waitcnt vmcnt(0)
	v_pk_mul_f32 v[92:93], v[92:93], s[8:9] op_sel_hi:[1,0]
	s_nop 0
	v_pk_fma_f32 v[64:65], v[64:65], v[20:21], v[92:93]
	v_pk_mul_f32 v[92:93], v[94:95], s[8:9] op_sel_hi:[1,0]
	s_nop 0
	v_pk_fma_f32 v[66:67], v[66:67], v[22:23], v[92:93]
	global_store_dwordx4 v[98:99], v[64:67], off offset:192
	s_nop 0
	v_ashrrev_i32_e32 v97, 31, v96
	v_lshlrev_b64 v[64:65], 12, v[96:97]
	v_lshl_add_u64 v[64:65], s[44:45], 0, v[64:65]
	v_lshl_add_u64 v[64:65], v[64:65], 0, v[78:79]
	v_lshl_add_u64 v[92:93], v[64:65], 0, v[76:77]
	global_load_dwordx4 v[64:67], v[92:93], off
	s_waitcnt vmcnt(0)
	v_pk_mul_f32 v[64:65], v[64:65], s[8:9] op_sel_hi:[1,0]
	s_nop 0
	v_pk_fma_f32 v[60:61], v[60:61], v[32:33], v[64:65]
	v_pk_mul_f32 v[64:65], v[66:67], s[8:9] op_sel_hi:[1,0]
	s_nop 0
	v_pk_fma_f32 v[62:63], v[62:63], v[34:35], v[64:65]
	global_store_dwordx4 v[92:93], v[60:63], off
	global_load_dwordx4 v[60:63], v[92:93], off offset:64
	s_waitcnt vmcnt(0)
	v_pk_mul_f32 v[60:61], v[60:61], s[8:9] op_sel_hi:[1,0]
	s_nop 0
	v_pk_fma_f32 v[56:57], v[56:57], v[28:29], v[60:61]
	v_pk_mul_f32 v[60:61], v[62:63], s[8:9] op_sel_hi:[1,0]
	s_nop 0
	v_pk_fma_f32 v[58:59], v[58:59], v[30:31], v[60:61]
	global_store_dwordx4 v[92:93], v[56:59], off offset:64
	global_load_dwordx4 v[56:59], v[92:93], off offset:128
	s_waitcnt vmcnt(0)
	v_pk_mul_f32 v[56:57], v[56:57], s[8:9] op_sel_hi:[1,0]
	s_nop 0
	v_pk_fma_f32 v[52:53], v[52:53], v[24:25], v[56:57]
	v_pk_mul_f32 v[56:57], v[58:59], s[8:9] op_sel_hi:[1,0]
	s_nop 0
	v_pk_fma_f32 v[54:55], v[54:55], v[26:27], v[56:57]
	global_store_dwordx4 v[92:93], v[52:55], off offset:128
	global_load_dwordx4 v[52:55], v[92:93], off offset:192
	s_waitcnt vmcnt(0)
	v_pk_mul_f32 v[52:53], v[52:53], s[8:9] op_sel_hi:[1,0]
	s_nop 0
	v_pk_fma_f32 v[48:49], v[48:49], v[20:21], v[52:53]
	v_pk_mul_f32 v[52:53], v[54:55], s[8:9] op_sel_hi:[1,0]
	s_nop 0
	v_pk_fma_f32 v[50:51], v[50:51], v[22:23], v[52:53]
	global_store_dwordx4 v[92:93], v[48:51], off offset:192
	s_nop 0
	v_ashrrev_i32_e32 v83, 31, v82
	v_lshlrev_b64 v[48:49], 12, v[82:83]
	v_lshl_add_u64 v[48:49], s[44:45], 0, v[48:49]
	v_lshl_add_u64 v[48:49], v[48:49], 0, v[78:79]
	v_lshl_add_u64 v[52:53], v[48:49], 0, v[76:77]
	global_load_dwordx4 v[48:51], v[52:53], off
	s_waitcnt vmcnt(0)
	v_pk_mul_f32 v[48:49], v[48:49], s[8:9] op_sel_hi:[1,0]
	s_nop 0
	v_pk_fma_f32 v[44:45], v[44:45], v[32:33], v[48:49]
	v_pk_mul_f32 v[48:49], v[50:51], s[8:9] op_sel_hi:[1,0]
	s_nop 0
	v_pk_fma_f32 v[46:47], v[46:47], v[34:35], v[48:49]
	global_store_dwordx4 v[52:53], v[44:47], off
	global_load_dwordx4 v[44:47], v[52:53], off offset:64
	s_waitcnt vmcnt(0)
	v_pk_mul_f32 v[44:45], v[44:45], s[8:9] op_sel_hi:[1,0]
	s_nop 0
	v_pk_fma_f32 v[40:41], v[40:41], v[28:29], v[44:45]
	v_pk_mul_f32 v[44:45], v[46:47], s[8:9] op_sel_hi:[1,0]
	s_nop 0
	v_pk_fma_f32 v[42:43], v[42:43], v[30:31], v[44:45]
	global_store_dwordx4 v[52:53], v[40:43], off offset:64
	global_load_dwordx4 v[40:43], v[52:53], off offset:128
	s_waitcnt vmcnt(0)
	v_pk_mul_f32 v[40:41], v[40:41], s[8:9] op_sel_hi:[1,0]
	s_nop 0
	v_pk_fma_f32 v[36:37], v[36:37], v[24:25], v[40:41]
	v_pk_mul_f32 v[40:41], v[42:43], s[8:9] op_sel_hi:[1,0]
	s_nop 0
	v_pk_fma_f32 v[38:39], v[38:39], v[26:27], v[40:41]
	global_store_dwordx4 v[52:53], v[36:39], off offset:128
	global_load_dwordx4 v[36:39], v[52:53], off offset:192
	s_waitcnt vmcnt(0)
	v_pk_mul_f32 v[36:37], v[36:37], s[8:9] op_sel_hi:[1,0]
	s_nop 0
	v_pk_fma_f32 v[16:17], v[16:17], v[20:21], v[36:37]
	v_pk_mul_f32 v[36:37], v[38:39], s[8:9] op_sel_hi:[1,0]
	s_nop 0
	v_pk_fma_f32 v[18:19], v[18:19], v[22:23], v[36:37]
	global_store_dwordx4 v[52:53], v[16:19], off offset:192
	s_nop 0
	v_ashrrev_i32_e32 v81, 31, v80
	v_lshlrev_b64 v[16:17], 12, v[80:81]
	v_lshl_add_u64 v[16:17], s[44:45], 0, v[16:17]
	v_lshl_add_u64 v[16:17], v[16:17], 0, v[78:79]
	v_lshl_add_u64 v[36:37], v[16:17], 0, v[76:77]
	global_load_dwordx4 v[16:19], v[36:37], off
	s_waitcnt vmcnt(0)
	v_pk_mul_f32 v[16:17], v[16:17], s[8:9] op_sel_hi:[1,0]
	s_nop 0
	v_pk_fma_f32 v[12:13], v[12:13], v[32:33], v[16:17]
	v_pk_mul_f32 v[16:17], v[18:19], s[8:9] op_sel_hi:[1,0]
	s_nop 0
	v_pk_fma_f32 v[14:15], v[14:15], v[34:35], v[16:17]
	global_store_dwordx4 v[36:37], v[12:15], off
	global_load_dwordx4 v[12:15], v[36:37], off offset:64
	s_waitcnt vmcnt(0)
	v_pk_mul_f32 v[12:13], v[12:13], s[8:9] op_sel_hi:[1,0]
	s_nop 0
	v_pk_fma_f32 v[8:9], v[8:9], v[28:29], v[12:13]
	v_pk_mul_f32 v[12:13], v[14:15], s[8:9] op_sel_hi:[1,0]
	s_nop 0
	v_pk_fma_f32 v[10:11], v[10:11], v[30:31], v[12:13]
	global_store_dwordx4 v[36:37], v[8:11], off offset:64
	global_load_dwordx4 v[8:11], v[36:37], off offset:128
	s_waitcnt vmcnt(0)
	v_pk_mul_f32 v[8:9], v[8:9], s[8:9] op_sel_hi:[1,0]
	s_nop 0
	v_pk_fma_f32 v[4:5], v[4:5], v[24:25], v[8:9]
	v_pk_mul_f32 v[8:9], v[10:11], s[8:9] op_sel_hi:[1,0]
	s_nop 0
	v_pk_fma_f32 v[6:7], v[6:7], v[26:27], v[8:9]
	global_store_dwordx4 v[36:37], v[4:7], off offset:128
	global_load_dwordx4 v[4:7], v[36:37], off offset:192
	s_waitcnt vmcnt(0)
	v_pk_mul_f32 v[4:5], v[4:5], s[8:9] op_sel_hi:[1,0]
	s_nop 0
	v_pk_fma_f32 v[0:1], v[0:1], v[20:21], v[4:5]
	v_pk_mul_f32 v[4:5], v[6:7], s[8:9] op_sel_hi:[1,0]
	s_nop 0
	v_pk_fma_f32 v[2:3], v[2:3], v[22:23], v[4:5]
	global_store_dwordx4 v[36:37], v[0:3], off offset:192
	s_cbranch_scc0 .LBB0_1405

.LBB0_1577:
	s_lshl_b32 s36, s35, 14
	s_waitcnt vmcnt(0)
	v_lshl_add_u64 v[80:81], v[66:67], 0, s[16:17]
	s_add_i32 s36, s19, s36
	s_waitcnt lgkmcnt(0)
	s_barrier
	v_lshl_add_u64 v[76:77], v[80:81], 0, s[6:7]
	s_mov_b32 m0, s36
	v_lshl_add_u64 v[118:119], v[64:65], 0, s[16:17]
	global_load_lds_dwordx4 v[76:77], off
	v_lshl_add_u64 v[76:77], v[80:81], 0, s[8:9]
	s_add_i32 m0, s36, 0x400
	s_nop 0
	global_load_lds_dwordx4 v[76:77], off
	s_add_i32 m0, s36, 0x2000
	v_lshl_add_u64 v[76:77], v[118:119], 0, s[6:7]
	global_load_lds_dwordx4 v[76:77], off
	s_add_i32 m0, s36, 0x2400
	s_lshl_b32 s36, s34, 14
	v_add_u32_e32 v120, s36, v86
	v_or_b32_e32 v121, s36, v87
	s_add_i32 s36, s34, 1
	s_cmp_lg_u32 s34, 3
	s_cselect_b32 s34, s36, 0
	s_add_i32 s36, s35, 1
	v_lshl_add_u64 v[76:77], v[118:119], 0, s[8:9]
	s_cmp_lg_u32 s35, 3
	global_load_lds_dwordx4 v[76:77], off
	s_cselect_b32 s35, s36, 0
	ds_read_b128 v[76:79], v120
	ds_read_b128 v[90:93], v120 offset:1024
	ds_read_b128 v[94:97], v120 offset:2048
	ds_read_b128 v[98:101], v120 offset:3072
	ds_read_b128 v[102:105], v121
	ds_read_b128 v[106:109], v121 offset:1024
	ds_read_b128 v[110:113], v121 offset:2048
	ds_read_b128 v[114:117], v121 offset:3072
	s_lshl_b32 s98, s34, 14
	v_add_u32_e32 v158, s98, v86
	v_or_b32_e32 v159, s98, v87
	ds_read_b128 v[126:129], v158
	ds_read_b128 v[130:133], v158 offset:1024
	ds_read_b128 v[134:137], v158 offset:2048
	ds_read_b128 v[138:141], v158 offset:3072
	ds_read_b128 v[142:145], v159
	ds_read_b128 v[146:149], v159 offset:1024
	ds_read_b128 v[150:153], v159 offset:2048
	ds_read_b128 v[154:157], v159 offset:3072
	s_waitcnt lgkmcnt(8)
	s_lshl_b32 s36, s35, 14
	s_add_i32 s36, s19, s36
	v_mfma_f32_16x16x32_bf16 v[60:63], v[102:105], v[76:79], v[60:63]
	v_mfma_f32_16x16x32_bf16 v[56:59], v[106:109], v[76:79], v[56:59]
	s_mov_b32 m0, s36
	v_mfma_f32_16x16x32_bf16 v[52:55], v[110:113], v[76:79], v[52:55]
	v_mfma_f32_16x16x32_bf16 v[48:51], v[114:117], v[76:79], v[48:51]
	v_lshl_add_u64 v[76:77], v[80:81], 0, s[10:11]
	global_load_lds_dwordx4 v[76:77], off
	v_lshl_add_u64 v[76:77], v[80:81], 0, s[12:13]
	s_add_i32 m0, s36, 0x400
	v_mfma_f32_16x16x32_bf16 v[44:47], v[102:105], v[90:93], v[44:47]
	global_load_lds_dwordx4 v[76:77], off
	s_add_i32 m0, s36, 0x2000
	v_lshl_add_u64 v[76:77], v[118:119], 0, s[10:11]
	global_load_lds_dwordx4 v[76:77], off
	v_lshl_add_u64 v[76:77], v[118:119], 0, s[12:13]
	s_add_i32 m0, s36, 0x2400
	v_mfma_f32_16x16x32_bf16 v[40:43], v[106:109], v[90:93], v[40:43]
	global_load_lds_dwordx4 v[76:77], off
	s_lshl_b32 s36, s34, 14
	v_mfma_f32_16x16x32_bf16 v[36:39], v[110:113], v[90:93], v[36:39]
	v_add_u32_e32 v80, s36, v86
	v_or_b32_e32 v81, s36, v87
	s_add_i32 s36, s34, 1
	v_mfma_f32_16x16x32_bf16 v[32:35], v[114:117], v[90:93], v[32:35]
	s_cmp_lg_u32 s34, 3
	s_cselect_b32 s34, s36, 0
	s_add_i32 s36, s35, 1
	v_mfma_f32_16x16x32_bf16 v[28:31], v[102:105], v[94:97], v[28:31]
	s_cmp_lg_u32 s35, 3
	s_cselect_b32 s35, s36, 0
	s_add_u32 s16, s16, 0x80
	v_mfma_f32_16x16x32_bf16 v[24:27], v[106:109], v[94:97], v[24:27]
	s_addc_u32 s17, s17, 0
	s_cmpk_eq_i32 s16, 0x1580
	v_mfma_f32_16x16x32_bf16 v[20:23], v[110:113], v[94:97], v[20:23]
	v_mfma_f32_16x16x32_bf16 v[16:19], v[114:117], v[94:97], v[16:19]
	v_mfma_f32_16x16x32_bf16 v[12:15], v[102:105], v[98:101], v[12:15]
	v_mfma_f32_16x16x32_bf16 v[8:11], v[106:109], v[98:101], v[8:11]
	v_mfma_f32_16x16x32_bf16 v[4:7], v[110:113], v[98:101], v[4:7]
	v_mfma_f32_16x16x32_bf16 v[0:3], v[114:117], v[98:101], v[0:3]
	s_waitcnt lgkmcnt(0)
	s_nop 0
	v_mfma_f32_16x16x32_bf16 v[60:63], v[142:145], v[126:129], v[60:63]
	v_mfma_f32_16x16x32_bf16 v[56:59], v[146:149], v[126:129], v[56:59]
	v_mfma_f32_16x16x32_bf16 v[52:55], v[150:153], v[126:129], v[52:55]
	v_mfma_f32_16x16x32_bf16 v[48:51], v[154:157], v[126:129], v[48:51]
	v_mfma_f32_16x16x32_bf16 v[44:47], v[142:145], v[130:133], v[44:47]
	v_mfma_f32_16x16x32_bf16 v[40:43], v[146:149], v[130:133], v[40:43]
	v_mfma_f32_16x16x32_bf16 v[36:39], v[150:153], v[130:133], v[36:39]
	v_mfma_f32_16x16x32_bf16 v[32:35], v[154:157], v[130:133], v[32:35]
	v_mfma_f32_16x16x32_bf16 v[28:31], v[142:145], v[134:137], v[28:31]
	v_mfma_f32_16x16x32_bf16 v[24:27], v[146:149], v[134:137], v[24:27]
	v_mfma_f32_16x16x32_bf16 v[20:23], v[150:153], v[134:137], v[20:23]
	v_mfma_f32_16x16x32_bf16 v[16:19], v[154:157], v[134:137], v[16:19]
	v_mfma_f32_16x16x32_bf16 v[12:15], v[142:145], v[138:141], v[12:15]
	v_mfma_f32_16x16x32_bf16 v[8:11], v[146:149], v[138:141], v[8:11]
	v_mfma_f32_16x16x32_bf16 v[4:7], v[150:153], v[138:141], v[4:7]
	v_mfma_f32_16x16x32_bf16 v[0:3], v[154:157], v[138:141], v[0:3]
	s_cbranch_scc0 .LBB0_1577
	s_waitcnt vmcnt(4)
	s_waitcnt lgkmcnt(0)
	s_barrier
	ds_read_b128 v[64:67], v86 offset:32768
	ds_read_b128 v[76:79], v86 offset:33792
	ds_read_b128 v[90:93], v86 offset:34816
	ds_read_b128 v[94:97], v86 offset:35840
	ds_read_b128 v[98:101], v87 offset:32768
	ds_read_b128 v[102:105], v87 offset:33792
	ds_read_b128 v[106:109], v87 offset:34816
	ds_read_b128 v[110:113], v87 offset:35840
	s_waitcnt lgkmcnt(0)
	s_waitcnt vmcnt(0)
	s_waitcnt lgkmcnt(0)
	s_barrier
	v_mfma_f32_16x16x32_bf16 v[56:59], v[102:105], v[64:67], v[56:59]
	s_movk_i32 s16, 0xfff
	v_readlane_b32 s36, v241, 1
	v_mfma_f32_16x16x32_bf16 v[40:43], v[102:105], v[76:79], v[40:43]
	v_readlane_b32 s44, v241, 9
	v_readlane_b32 s45, v241, 10
	s_add_i32 s2, s2, s3
	v_mfma_f32_16x16x32_bf16 v[24:27], v[102:105], v[90:93], v[24:27]
	s_add_i32 s20, s20, s21
	v_readlane_b32 s37, v241, 2
	v_readlane_b32 s38, v241, 3
	v_mfma_f32_16x16x32_bf16 v[52:55], v[106:109], v[64:67], v[52:55]
	v_readlane_b32 s39, v241, 4
	v_readlane_b32 s40, v241, 5
	v_readlane_b32 s41, v241, 6
	v_mfma_f32_16x16x32_bf16 v[36:39], v[106:109], v[76:79], v[36:39]
	v_readlane_b32 s42, v241, 7
	v_readlane_b32 s43, v241, 8
	v_readlane_b32 s46, v241, 11
	v_mfma_f32_16x16x32_bf16 v[20:23], v[106:109], v[90:93], v[20:23]
	v_readlane_b32 s47, v241, 12
	v_readlane_b32 s48, v241, 13
	v_readlane_b32 s49, v241, 14
	v_mfma_f32_16x16x32_bf16 v[60:63], v[98:101], v[64:67], v[60:63]
	v_readlane_b32 s50, v241, 15
	v_readlane_b32 s51, v241, 16
	v_mfma_f32_16x16x32_bf16 v[48:51], v[110:113], v[64:67], v[48:51]
	v_mfma_f32_16x16x32_bf16 v[44:47], v[98:101], v[76:79], v[44:47]
	v_mfma_f32_16x16x32_bf16 v[32:35], v[110:113], v[76:79], v[32:35]
	v_mfma_f32_16x16x32_bf16 v[28:31], v[98:101], v[90:93], v[28:31]
	v_mfma_f32_16x16x32_bf16 v[16:19], v[110:113], v[90:93], v[16:19]
	v_mfma_f32_16x16x32_bf16 v[12:15], v[98:101], v[94:97], v[12:15]
	v_mfma_f32_16x16x32_bf16 v[8:11], v[102:105], v[94:97], v[8:11]
	v_mfma_f32_16x16x32_bf16 v[4:7], v[106:109], v[94:97], v[4:7]
	v_mfma_f32_16x16x32_bf16 v[0:3], v[110:113], v[94:97], v[0:3]
	ds_read_b128 v[64:67], v86 offset:49152
	ds_read_b128 v[76:79], v86 offset:50176
	ds_read_b128 v[90:93], v86 offset:51200
	ds_read_b128 v[94:97], v86 offset:52224
	ds_read_b128 v[98:101], v87 offset:49152
	ds_read_b128 v[102:105], v87 offset:50176
	ds_read_b128 v[106:109], v87 offset:51200
	ds_read_b128 v[110:113], v87 offset:52224
	s_waitcnt lgkmcnt(0)
	s_waitcnt lgkmcnt(0)
	s_barrier
	v_mfma_f32_16x16x32_bf16 v[118:121], v[102:105], v[64:67], v[56:59]
	v_mfma_f32_16x16x32_bf16 v[56:59], v[102:105], v[76:79], v[40:43]
	v_mfma_f32_16x16x32_bf16 v[40:43], v[102:105], v[90:93], v[24:27]
	s_nop 2
	v_add_u32_e32 v24, s31, v84
	v_mfma_f32_16x16x32_bf16 v[122:125], v[106:109], v[64:67], v[52:55]
	v_cmp_lt_i32_e32 vcc, s16, v24
	s_movk_i32 s16, 0x6000
	v_mfma_f32_16x16x32_bf16 v[52:55], v[106:109], v[76:79], v[36:39]
	v_mfma_f32_16x16x32_bf16 v[36:39], v[106:109], v[90:93], v[20:23]
	s_nop 2
	v_add_u32_e32 v21, 0xfffff000, v24
	v_lshrrev_b32_e32 v21, 12, v21
	v_add_u32_e32 v21, 1, v21
	v_or_b32_e32 v20, s33, v85
	v_cndmask_b32_e32 v21, 0, v21, vcc
	v_mad_u64_u32 v[22:23], s[16:17], v21, s16, v[74:75]
	v_ashrrev_i32_e32 v21, 31, v20
	v_mfma_f32_16x16x32_bf16 v[114:117], v[98:101], v[64:67], v[60:63]
	s_mov_b64 s[16:17], 0x5000
	v_mfma_f32_16x16x32_bf16 v[64:67], v[110:113], v[64:67], v[48:51]
	v_mfma_f32_16x16x32_bf16 v[60:63], v[98:101], v[76:79], v[44:47]
	v_mfma_f32_16x16x32_bf16 v[48:51], v[110:113], v[76:79], v[32:35]
	v_lshlrev_b64 v[76:77], 2, v[20:21]
	v_lshl_add_u64 v[20:21], v[22:23], 0, v[76:77]
	v_lshl_add_u64 v[20:21], v[20:21], 0, v[68:69]
	v_lshl_add_u64 v[22:23], v[20:21], 0, s[16:17]
	s_movk_i32 s16, 0x5000
	v_add_co_u32_e32 v20, vcc, s16, v20
	v_mfma_f32_16x16x32_bf16 v[44:47], v[98:101], v[90:93], v[28:31]
	s_nop 0
	v_addc_co_u32_e32 v21, vcc, 0, v21, vcc
	v_mfma_f32_16x16x32_bf16 v[16:19], v[110:113], v[90:93], v[16:19]
	v_or_b32_e32 v90, v24, v82
	v_or_b32_e32 v80, 32, v90
	v_or_b32_e32 v78, 48, v90
	v_mfma_f32_16x16x32_bf16 v[12:15], v[98:101], v[94:97], v[12:15]
	global_load_dwordx4 v[32:35], v[20:21], off
	global_load_dwordx4 v[28:31], v[22:23], off offset:64
	global_load_dwordx4 v[24:27], v[22:23], off offset:128
	s_nop 0
	global_load_dwordx4 v[20:23], v[22:23], off offset:192
	v_mfma_f32_16x16x32_bf16 v[8:11], v[102:105], v[94:97], v[8:11]
	v_mfma_f32_16x16x32_bf16 v[4:7], v[106:109], v[94:97], v[4:7]
	v_mfma_f32_16x16x32_bf16 v[0:3], v[110:113], v[94:97], v[0:3]
	v_or_b32_e32 v94, 16, v90
	s_nop 0
	v_ashrrev_i32_e32 v91, 31, v90
	v_lshlrev_b64 v[90:91], 12, v[90:91]
	v_lshl_add_u64 v[90:91], s[44:45], 0, v[90:91]
	v_lshl_add_u64 v[90:91], v[90:91], 0, v[76:77]
	v_lshl_add_u64 v[96:97], v[90:91], 0, v[68:69]
	global_load_dwordx4 v[90:93], v[96:97], off
	s_waitcnt vmcnt(0)
	v_pk_mul_f32 v[90:91], v[90:91], s[14:15] op_sel_hi:[1,0]
	v_pk_mul_f32 v[92:93], v[92:93], s[14:15] op_sel_hi:[1,0]
	v_pk_fma_f32 v[90:91], v[114:115], v[32:33], v[90:91]
	v_pk_fma_f32 v[92:93], v[116:117], v[34:35], v[92:93]
	global_store_dwordx4 v[96:97], v[90:93], off
	global_load_dwordx4 v[90:93], v[96:97], off offset:64
	s_waitcnt vmcnt(0)
	v_pk_mul_f32 v[90:91], v[90:91], s[14:15] op_sel_hi:[1,0]
	v_pk_mul_f32 v[92:93], v[92:93], s[14:15] op_sel_hi:[1,0]
	v_pk_fma_f32 v[90:91], v[118:119], v[28:29], v[90:91]
	v_pk_fma_f32 v[92:93], v[120:121], v[30:31], v[92:93]
	global_store_dwordx4 v[96:97], v[90:93], off offset:64
	global_load_dwordx4 v[90:93], v[96:97], off offset:128
	s_waitcnt vmcnt(0)
	v_pk_mul_f32 v[90:91], v[90:91], s[14:15] op_sel_hi:[1,0]
	v_pk_mul_f32 v[92:93], v[92:93], s[14:15] op_sel_hi:[1,0]
	v_pk_fma_f32 v[90:91], v[122:123], v[24:25], v[90:91]
	v_pk_fma_f32 v[92:93], v[124:125], v[26:27], v[92:93]
	global_store_dwordx4 v[96:97], v[90:93], off offset:128
	global_load_dwordx4 v[90:93], v[96:97], off offset:192
	s_waitcnt vmcnt(0)
	v_pk_mul_f32 v[90:91], v[90:91], s[14:15] op_sel_hi:[1,0]
	s_nop 0
	v_pk_fma_f32 v[64:65], v[64:65], v[20:21], v[90:91]
	v_pk_mul_f32 v[90:91], v[92:93], s[14:15] op_sel_hi:[1,0]
	s_nop 0
	v_pk_fma_f32 v[66:67], v[66:67], v[22:23], v[90:91]
	global_store_dwordx4 v[96:97], v[64:67], off offset:192
	s_nop 0
	v_ashrrev_i32_e32 v95, 31, v94
	v_lshlrev_b64 v[64:65], 12, v[94:95]
	v_lshl_add_u64 v[64:65], s[44:45], 0, v[64:65]
	v_lshl_add_u64 v[64:65], v[64:65], 0, v[76:77]
	v_lshl_add_u64 v[90:91], v[64:65], 0, v[68:69]
	global_load_dwordx4 v[64:67], v[90:91], off
	s_waitcnt vmcnt(0)
	v_pk_mul_f32 v[64:65], v[64:65], s[14:15] op_sel_hi:[1,0]
	s_nop 0
	v_pk_fma_f32 v[60:61], v[60:61], v[32:33], v[64:65]
	v_pk_mul_f32 v[64:65], v[66:67], s[14:15] op_sel_hi:[1,0]
	s_nop 0
	v_pk_fma_f32 v[62:63], v[62:63], v[34:35], v[64:65]
	global_store_dwordx4 v[90:91], v[60:63], off
	global_load_dwordx4 v[60:63], v[90:91], off offset:64
	s_waitcnt vmcnt(0)
	v_pk_mul_f32 v[60:61], v[60:61], s[14:15] op_sel_hi:[1,0]
	s_nop 0
	v_pk_fma_f32 v[56:57], v[56:57], v[28:29], v[60:61]
	v_pk_mul_f32 v[60:61], v[62:63], s[14:15] op_sel_hi:[1,0]
	s_nop 0
	v_pk_fma_f32 v[58:59], v[58:59], v[30:31], v[60:61]
	global_store_dwordx4 v[90:91], v[56:59], off offset:64
	global_load_dwordx4 v[56:59], v[90:91], off offset:128
	s_waitcnt vmcnt(0)
	v_pk_mul_f32 v[56:57], v[56:57], s[14:15] op_sel_hi:[1,0]
	s_nop 0
	v_pk_fma_f32 v[52:53], v[52:53], v[24:25], v[56:57]
	v_pk_mul_f32 v[56:57], v[58:59], s[14:15] op_sel_hi:[1,0]
	s_nop 0
	v_pk_fma_f32 v[54:55], v[54:55], v[26:27], v[56:57]
	global_store_dwordx4 v[90:91], v[52:55], off offset:128
	global_load_dwordx4 v[52:55], v[90:91], off offset:192
	s_waitcnt vmcnt(0)
	v_pk_mul_f32 v[52:53], v[52:53], s[14:15] op_sel_hi:[1,0]
	s_nop 0
	v_pk_fma_f32 v[48:49], v[48:49], v[20:21], v[52:53]
	v_pk_mul_f32 v[52:53], v[54:55], s[14:15] op_sel_hi:[1,0]
	s_nop 0
	v_pk_fma_f32 v[50:51], v[50:51], v[22:23], v[52:53]
	global_store_dwordx4 v[90:91], v[48:51], off offset:192
	s_nop 0
	v_ashrrev_i32_e32 v81, 31, v80
	v_lshlrev_b64 v[48:49], 12, v[80:81]
	v_lshl_add_u64 v[48:49], s[44:45], 0, v[48:49]
	v_lshl_add_u64 v[48:49], v[48:49], 0, v[76:77]
	v_lshl_add_u64 v[52:53], v[48:49], 0, v[68:69]
	global_load_dwordx4 v[48:51], v[52:53], off
	s_waitcnt vmcnt(0)
	v_pk_mul_f32 v[48:49], v[48:49], s[14:15] op_sel_hi:[1,0]
	s_nop 0
	v_pk_fma_f32 v[44:45], v[44:45], v[32:33], v[48:49]
	v_pk_mul_f32 v[48:49], v[50:51], s[14:15] op_sel_hi:[1,0]
	s_nop 0
	v_pk_fma_f32 v[46:47], v[46:47], v[34:35], v[48:49]
	global_store_dwordx4 v[52:53], v[44:47], off
	global_load_dwordx4 v[44:47], v[52:53], off offset:64
	s_waitcnt vmcnt(0)
	v_pk_mul_f32 v[44:45], v[44:45], s[14:15] op_sel_hi:[1,0]
	s_nop 0
	v_pk_fma_f32 v[40:41], v[40:41], v[28:29], v[44:45]
	v_pk_mul_f32 v[44:45], v[46:47], s[14:15] op_sel_hi:[1,0]
	s_nop 0
	v_pk_fma_f32 v[42:43], v[42:43], v[30:31], v[44:45]
	global_store_dwordx4 v[52:53], v[40:43], off offset:64
	global_load_dwordx4 v[40:43], v[52:53], off offset:128
	s_waitcnt vmcnt(0)
	v_pk_mul_f32 v[40:41], v[40:41], s[14:15] op_sel_hi:[1,0]
	s_nop 0
	v_pk_fma_f32 v[36:37], v[36:37], v[24:25], v[40:41]
	v_pk_mul_f32 v[40:41], v[42:43], s[14:15] op_sel_hi:[1,0]
	s_nop 0
	v_pk_fma_f32 v[38:39], v[38:39], v[26:27], v[40:41]
	global_store_dwordx4 v[52:53], v[36:39], off offset:128
	global_load_dwordx4 v[36:39], v[52:53], off offset:192
	s_waitcnt vmcnt(0)
	v_pk_mul_f32 v[36:37], v[36:37], s[14:15] op_sel_hi:[1,0]
	s_nop 0
	v_pk_fma_f32 v[16:17], v[16:17], v[20:21], v[36:37]
	v_pk_mul_f32 v[36:37], v[38:39], s[14:15] op_sel_hi:[1,0]
	s_nop 0
	v_pk_fma_f32 v[18:19], v[18:19], v[22:23], v[36:37]
	global_store_dwordx4 v[52:53], v[16:19], off offset:192
	s_nop 0
	v_ashrrev_i32_e32 v79, 31, v78
	v_lshlrev_b64 v[16:17], 12, v[78:79]
	v_lshl_add_u64 v[16:17], s[44:45], 0, v[16:17]
	v_lshl_add_u64 v[16:17], v[16:17], 0, v[76:77]
	v_lshl_add_u64 v[36:37], v[16:17], 0, v[68:69]
	global_load_dwordx4 v[16:19], v[36:37], off
	s_waitcnt vmcnt(0)
	v_pk_mul_f32 v[16:17], v[16:17], s[14:15] op_sel_hi:[1,0]
	s_nop 0
	v_pk_fma_f32 v[12:13], v[12:13], v[32:33], v[16:17]
	v_pk_mul_f32 v[16:17], v[18:19], s[14:15] op_sel_hi:[1,0]
	s_nop 0
	v_pk_fma_f32 v[14:15], v[14:15], v[34:35], v[16:17]
	global_store_dwordx4 v[36:37], v[12:15], off
	global_load_dwordx4 v[12:15], v[36:37], off offset:64
	s_waitcnt vmcnt(0)
	v_pk_mul_f32 v[12:13], v[12:13], s[14:15] op_sel_hi:[1,0]
	s_nop 0
	v_pk_fma_f32 v[8:9], v[8:9], v[28:29], v[12:13]
	v_pk_mul_f32 v[12:13], v[14:15], s[14:15] op_sel_hi:[1,0]
	s_nop 0
	v_pk_fma_f32 v[10:11], v[10:11], v[30:31], v[12:13]
	global_store_dwordx4 v[36:37], v[8:11], off offset:64
	global_load_dwordx4 v[8:11], v[36:37], off offset:128
	s_waitcnt vmcnt(0)
	v_pk_mul_f32 v[8:9], v[8:9], s[14:15] op_sel_hi:[1,0]
	s_nop 0
	v_pk_fma_f32 v[4:5], v[4:5], v[24:25], v[8:9]
	v_pk_mul_f32 v[8:9], v[10:11], s[14:15] op_sel_hi:[1,0]
	s_nop 0
	v_pk_fma_f32 v[6:7], v[6:7], v[26:27], v[8:9]
	global_store_dwordx4 v[36:37], v[4:7], off offset:128
	global_load_dwordx4 v[4:7], v[36:37], off offset:192
	s_waitcnt vmcnt(0)
	v_pk_mul_f32 v[4:5], v[4:5], s[14:15] op_sel_hi:[1,0]
	s_nop 0
	v_pk_fma_f32 v[0:1], v[0:1], v[20:21], v[4:5]
	v_pk_mul_f32 v[4:5], v[6:7], s[14:15] op_sel_hi:[1,0]
	s_add_i32 s15, s15, s30
	v_pk_fma_f32 v[2:3], v[2:3], v[22:23], v[4:5]
	s_cmpk_gt_i32 s2, 0x9f
	global_store_dwordx4 v[36:37], v[0:3], off offset:192
	s_cbranch_scc0 .LBB0_1576

.LBB0_2892:
	s_cmp_lt_u32 s46, 10
	s_cselect_b32 s52, s42, 0x500
	s_cselect_b32 s10, s57, s59
	s_cselect_b32 s49, s56, s58
	s_cselect_b32 s54, 0, 0xfffffe80
	v_mad_i64_i32 v[92:93], s[50:51], s52, v64, 0
	s_cselect_b32 s53, 0, -1
	v_mov_b32_e32 v90, s49
	v_mov_b32_e32 v91, s10
	s_add_u32 s50, s24, s54
	v_lshl_add_u64 v[90:91], v[92:93], 1, v[90:91]
	s_addc_u32 s51, s25, s53
	s_lshl_b32 s49, s47, 14
	v_lshl_add_u64 v[90:91], s[50:51], 1, v[90:91]
	s_waitcnt vmcnt(0)
	s_lshl_b32 s10, s52, 5
	s_add_i32 s49, s28, s49
	v_lshl_add_u64 v[120:121], v[90:91], 0, v[68:69]
	s_waitcnt lgkmcnt(0)
	s_barrier
	v_lshl_add_u64 v[90:91], v[120:121], 0, s[12:13]
	v_lshl_add_u64 v[122:123], v[120:121], 0, s[10:11]
	s_mov_b32 m0, s49
	v_lshl_add_u64 v[118:119], v[66:67], 0, s[26:27]
	global_load_lds_dwordx4 v[90:91], off
	v_lshl_add_u64 v[90:91], v[122:123], 0, s[12:13]
	s_add_i32 m0, s49, 0x400
	v_lshl_add_u64 v[78:79], v[118:119], 0, s[12:13]
	global_load_lds_dwordx4 v[90:91], off
	s_add_i32 m0, s49, 0x2000
	s_lshl_b32 s52, s48, 14
	global_load_lds_dwordx4 v[78:79], off
	s_add_i32 m0, s49, 0x2400
	s_add_i32 s10, s48, 1
	s_cmp_lg_u32 s48, 3
	s_cselect_b32 s10, s10, 0
	s_add_i32 s48, s47, 1
	v_lshl_add_u64 v[80:81], v[118:119], 0, s[14:15]
	s_cmp_lg_u32 s47, 3
	global_load_lds_dwordx4 v[80:81], off
	s_cselect_b32 s47, s48, 0
	v_add_u32_e32 v65, s52, v86
	v_or_b32_e32 v124, s52, v87
	ds_read_b128 v[78:81], v65
	ds_read_b128 v[90:93], v65 offset:1024
	ds_read_b128 v[94:97], v65 offset:2048
	ds_read_b128 v[98:101], v65 offset:3072
	ds_read_b128 v[102:105], v124
	ds_read_b128 v[106:109], v124 offset:1024
	ds_read_b128 v[110:113], v124 offset:2048
	ds_read_b128 v[114:117], v124 offset:3072
	s_lshl_b32 s98, s10, 14
	v_add_u32_e32 v200, s98, v86
	v_or_b32_e32 v201, s98, v87
	ds_read_b128 v[168:171], v200
	ds_read_b128 v[172:175], v200 offset:1024
	ds_read_b128 v[176:179], v200 offset:2048
	ds_read_b128 v[180:183], v200 offset:3072
	ds_read_b128 v[184:187], v201
	ds_read_b128 v[188:191], v201 offset:1024
	ds_read_b128 v[192:195], v201 offset:2048
	ds_read_b128 v[196:199], v201 offset:3072
	s_waitcnt lgkmcnt(8)
	s_lshl_b32 s48, s47, 14
	s_add_i32 s48, s28, s48
	v_mfma_f32_16x16x32_bf16 v[44:47], v[102:105], v[90:93], v[44:47]
	v_mfma_f32_16x16x32_bf16 v[40:43], v[106:109], v[90:93], v[40:43]
	s_mov_b32 m0, s48
	s_add_i32 s46, s46, 2
	v_mfma_f32_16x16x32_bf16 v[36:39], v[110:113], v[90:93], v[36:39]
	v_mfma_f32_16x16x32_bf16 v[32:35], v[114:117], v[90:93], v[32:35]
	v_lshl_add_u64 v[90:91], v[120:121], 0, s[16:17]
	v_lshl_add_u64 v[92:93], v[122:123], 0, s[16:17]
	global_load_lds_dwordx4 v[90:91], off
	s_add_i32 m0, s48, 0x400
	v_mfma_f32_16x16x32_bf16 v[60:63], v[102:105], v[78:81], v[60:63]
	global_load_lds_dwordx4 v[92:93], off
	s_add_i32 m0, s48, 0x2000
	v_mfma_f32_16x16x32_bf16 v[56:59], v[106:109], v[78:81], v[56:59]
	v_mfma_f32_16x16x32_bf16 v[52:55], v[110:113], v[78:81], v[52:55]
	v_mfma_f32_16x16x32_bf16 v[48:51], v[114:117], v[78:81], v[48:51]
	v_lshl_add_u64 v[78:79], v[118:119], 0, s[16:17]
	v_lshl_add_u64 v[80:81], v[118:119], 0, s[18:19]
	global_load_lds_dwordx4 v[78:79], off
	s_add_i32 m0, s48, 0x2400
	s_lshl_b32 s48, s10, 14
	global_load_lds_dwordx4 v[80:81], off
	v_add_u32_e32 v65, s48, v86
	v_or_b32_e32 v118, s48, v87
	s_add_i32 s48, s10, 1
	v_mfma_f32_16x16x32_bf16 v[28:31], v[102:105], v[94:97], v[28:31]
	s_cmp_lg_u32 s10, 3
	s_cselect_b32 s48, s48, 0
	s_add_i32 s10, s47, 1
	v_mfma_f32_16x16x32_bf16 v[20:23], v[106:109], v[94:97], v[20:23]
	s_cmp_lg_u32 s47, 3
	s_cselect_b32 s47, s10, 0
	s_add_u32 s26, s26, 0x80
	v_mfma_f32_16x16x32_bf16 v[16:19], v[110:113], v[94:97], v[16:19]
	s_addc_u32 s27, s27, 0
	s_add_u32 s24, s24, 64
	s_addc_u32 s25, s25, 0
	v_mfma_f32_16x16x32_bf16 v[12:15], v[114:117], v[94:97], v[12:15]
	s_cmpk_eq_i32 s26, 0x780
	v_mfma_f32_16x16x32_bf16 v[8:11], v[102:105], v[98:101], v[8:11]
	v_mfma_f32_16x16x32_bf16 v[4:7], v[106:109], v[98:101], v[4:7]
	v_mfma_f32_16x16x32_bf16 v[0:3], v[110:113], v[98:101], v[0:3]
	v_mfma_f32_16x16x32_bf16 v[24:27], v[114:117], v[98:101], v[24:27]
	s_waitcnt lgkmcnt(0)
	s_nop 0
	v_mfma_f32_16x16x32_bf16 v[60:63], v[184:187], v[168:171], v[60:63]
	v_mfma_f32_16x16x32_bf16 v[56:59], v[188:191], v[168:171], v[56:59]
	v_mfma_f32_16x16x32_bf16 v[52:55], v[192:195], v[168:171], v[52:55]
	v_mfma_f32_16x16x32_bf16 v[48:51], v[196:199], v[168:171], v[48:51]
	v_mfma_f32_16x16x32_bf16 v[44:47], v[184:187], v[172:175], v[44:47]
	v_mfma_f32_16x16x32_bf16 v[40:43], v[188:191], v[172:175], v[40:43]
	v_mfma_f32_16x16x32_bf16 v[36:39], v[192:195], v[172:175], v[36:39]
	v_mfma_f32_16x16x32_bf16 v[32:35], v[196:199], v[172:175], v[32:35]
	v_mfma_f32_16x16x32_bf16 v[28:31], v[184:187], v[176:179], v[28:31]
	v_mfma_f32_16x16x32_bf16 v[20:23], v[188:191], v[176:179], v[20:23]
	v_mfma_f32_16x16x32_bf16 v[16:19], v[192:195], v[176:179], v[16:19]
	v_mfma_f32_16x16x32_bf16 v[12:15], v[196:199], v[176:179], v[12:15]
	v_mfma_f32_16x16x32_bf16 v[8:11], v[184:187], v[180:183], v[8:11]
	v_mfma_f32_16x16x32_bf16 v[4:7], v[188:191], v[180:183], v[4:7]
	v_mfma_f32_16x16x32_bf16 v[0:3], v[192:195], v[180:183], v[0:3]
	v_mfma_f32_16x16x32_bf16 v[24:27], v[196:199], v[180:183], v[24:27]
	s_cbranch_scc0 .LBB0_2892
	s_waitcnt vmcnt(4)
	s_waitcnt lgkmcnt(0)
	s_barrier
	ds_read_b128 v[64:67], v86 offset:32768
	ds_read_b128 v[78:81], v86 offset:33792
	ds_read_b128 v[90:93], v86 offset:34816
	ds_read_b128 v[94:97], v86 offset:35840
	ds_read_b128 v[98:101], v87 offset:32768
	ds_read_b128 v[102:105], v87 offset:33792
	ds_read_b128 v[106:109], v87 offset:34816
	ds_read_b128 v[110:113], v87 offset:35840
	s_waitcnt lgkmcnt(0)
	s_waitcnt vmcnt(0)
	s_waitcnt lgkmcnt(0)
	s_barrier
	v_mfma_f32_16x16x32_bf16 v[158:161], v[102:105], v[90:93], v[20:23]
	s_add_i32 s2, s2, s3
	s_add_i32 s31, s31, s33
	v_mfma_f32_16x16x32_bf16 v[114:117], v[98:101], v[64:67], v[60:63]
	v_add_u32_e32 v22, s44, v84
	v_or_b32_e32 v20, s45, v85
	v_cmp_lt_i32_e32 vcc, s43, v22
	v_mfma_f32_16x16x32_bf16 v[118:121], v[102:105], v[64:67], v[56:59]
	v_ashrrev_i32_e32 v21, 31, v20
	v_readlane_b32 s44, v241, 1
	v_readlane_b32 s52, v241, 9
	v_mfma_f32_16x16x32_bf16 v[122:125], v[106:109], v[64:67], v[52:55]
	v_readlane_b32 s53, v241, 10
	s_cmpk_gt_i32 s2, 0x9f
	v_readlane_b32 s45, v241, 2
	v_mfma_f32_16x16x32_bf16 v[126:129], v[110:113], v[64:67], v[48:51]
	v_readlane_b32 s46, v241, 3
	v_readlane_b32 s47, v241, 4
	v_readlane_b32 s48, v241, 5
	v_mfma_f32_16x16x32_bf16 v[64:67], v[106:109], v[90:93], v[16:19]
	v_readlane_b32 s49, v241, 6
	v_readlane_b32 s50, v241, 7
	v_readlane_b32 s51, v241, 8
	v_add_u32_e32 v16, 0xfffff000, v22
	v_lshrrev_b32_e32 v16, 12, v16
	v_add_u32_e32 v16, 6, v16
	v_mfma_f32_16x16x32_bf16 v[60:63], v[110:113], v[90:93], v[12:15]
	v_readlane_b32 s54, v241, 11
	v_readlane_b32 s55, v241, 12
	v_readlane_b32 s56, v241, 13
	v_cndmask_b32_e32 v12, 5, v16, vcc
	v_mfma_f32_16x16x32_bf16 v[130:133], v[98:101], v[78:81], v[44:47]
	v_mad_u64_u32 v[12:13], s[24:25], v12, s30, v[74:75]
	v_readlane_b32 s57, v241, 14
	v_mfma_f32_16x16x32_bf16 v[134:137], v[102:105], v[78:81], v[40:43]
	v_readlane_b32 s58, v241, 15
	v_readlane_b32 s59, v241, 16
	v_mfma_f32_16x16x32_bf16 v[138:141], v[106:109], v[78:81], v[36:39]
	v_mfma_f32_16x16x32_bf16 v[142:145], v[110:113], v[78:81], v[32:35]
	v_lshlrev_b64 v[78:79], 2, v[20:21]
	v_mfma_f32_16x16x32_bf16 v[52:55], v[98:101], v[94:97], v[8:11]
	s_nop 2
	v_lshl_add_u64 v[8:9], v[12:13], 0, v[78:79]
	v_lshl_add_u64 v[8:9], v[8:9], 0, v[76:77]
	v_mfma_f32_16x16x32_bf16 v[146:149], v[98:101], v[90:93], v[28:31]
	ds_read_b128 v[150:153], v86 offset:49152
	ds_read_b128 v[154:157], v86 offset:50176
	ds_read_b128 v[56:59], v86 offset:51200
	ds_read_b128 v[28:31], v86 offset:52224
	ds_read_b128 v[44:47], v87 offset:49152
	ds_read_b128 v[40:43], v87 offset:50176
	ds_read_b128 v[36:39], v87 offset:51200
	ds_read_b128 v[32:35], v87 offset:52224
	s_waitcnt lgkmcnt(0)
	v_add_co_u32_e32 v14, vcc, s29, v8
	s_waitcnt lgkmcnt(0)
	s_barrier
	v_lshl_add_u64 v[12:13], v[8:9], 0, s[20:21]
	v_or_b32_e32 v98, v22, v82
	v_addc_co_u32_e32 v15, vcc, 0, v9, vcc
	v_mfma_f32_16x16x32_bf16 v[20:23], v[106:109], v[94:97], v[0:3]
	v_or_b32_e32 v162, 16, v98
	v_or_b32_e32 v164, 32, v98
	v_or_b32_e32 v80, 48, v98
	global_load_dwordx4 v[0:3], v[12:13], off offset:64
	global_load_dwordx4 v[8:11], v[12:13], off offset:128
	global_load_dwordx4 v[16:19], v[14:15], off
	s_nop 0
	global_load_dwordx4 v[12:15], v[12:13], off offset:192
	v_mfma_f32_16x16x32_bf16 v[48:51], v[102:105], v[94:97], v[4:7]
	v_ashrrev_i32_e32 v99, 31, v98
	v_mfma_f32_16x16x32_bf16 v[4:7], v[110:113], v[94:97], v[24:27]
	v_lshlrev_b64 v[94:95], 12, v[98:99]
	v_lshl_add_u64 v[98:99], s[52:53], 0, v[94:95]
	v_lshl_add_u64 v[98:99], v[98:99], 0, v[78:79]
	v_lshl_add_u64 v[166:167], v[98:99], 0, v[76:77]
	global_load_dwordx4 v[98:101], v[166:167], off
	v_mfma_f32_16x16x32_bf16 v[90:93], v[40:43], v[150:153], v[118:121]
	global_load_dwordx4 v[106:109], v[166:167], off offset:64
	global_load_dwordx4 v[110:113], v[166:167], off offset:128
	s_waitcnt vmcnt(0)
	v_pk_mul_f32 v[98:99], v[98:99], s[22:23] op_sel_hi:[1,0]
	global_load_dwordx4 v[118:121], v[166:167], off offset:192
	v_mfma_f32_16x16x32_bf16 v[24:27], v[44:47], v[150:153], v[114:117]
	v_mul_f32_e64 v100, v100, s22
	v_mul_f32_e64 v101, v101, s22
	v_pk_mul_f32 v[106:107], v[106:107], s[22:23] op_sel_hi:[1,0]
	v_pk_mul_f32 v[108:109], v[108:109], s[22:23] op_sel_hi:[1,0]
	v_mfma_f32_16x16x32_bf16 v[94:97], v[36:39], v[150:153], v[122:125]
	v_mul_f32_e64 v110, v110, s22
	v_mul_f32_e64 v111, v111, s22
	v_pk_mul_f32 v[112:113], v[112:113], s[22:23] op_sel_hi:[1,0]
	v_pk_fma_f32 v[24:25], v[24:25], v[16:17], v[98:99]
	v_mfma_f32_16x16x32_bf16 v[102:105], v[32:35], v[150:153], v[126:129]
	v_fma_f32 v26, v26, v18, v100
	v_fma_f32 v27, v27, v19, v101
	v_pk_fma_f32 v[90:91], v[90:91], v[0:1], v[106:107]
	v_pk_fma_f32 v[92:93], v[92:93], v[2:3], v[108:109]
	v_pk_fma_f32 v[94:95], v[94:95], v[8:9], v[110:111]
	v_pk_fma_f32 v[96:97], v[96:97], v[10:11], v[112:113]
	v_mfma_f32_16x16x32_bf16 v[114:117], v[44:47], v[154:157], v[130:133]
	s_waitcnt vmcnt(0)
	v_pk_mul_f32 v[118:119], v[118:119], s[22:23] op_sel_hi:[1,0]
	v_pk_mul_f32 v[120:121], v[120:121], s[22:23] op_sel_hi:[1,0]
	v_pk_fma_f32 v[98:99], v[102:103], v[12:13], v[118:119]
	v_pk_fma_f32 v[100:101], v[104:105], v[14:15], v[120:121]
	global_store_dwordx4 v[166:167], v[24:27], off
	global_store_dwordx4 v[166:167], v[90:93], off offset:64
	global_store_dwordx4 v[166:167], v[94:97], off offset:128
	global_store_dwordx4 v[166:167], v[98:101], off offset:192
	v_mfma_f32_16x16x32_bf16 v[122:125], v[40:43], v[154:157], v[134:137]
	v_ashrrev_i32_e32 v163, 31, v162
	v_lshlrev_b64 v[24:25], 12, v[162:163]
	v_lshl_add_u64 v[24:25], s[52:53], 0, v[24:25]
	v_lshl_add_u64 v[24:25], v[24:25], 0, v[78:79]
	v_lshl_add_u64 v[118:119], v[24:25], 0, v[76:77]
	global_load_dwordx4 v[24:27], v[118:119], off
	global_load_dwordx4 v[94:97], v[118:119], off offset:64
	global_load_dwordx4 v[98:101], v[118:119], off offset:128
	global_load_dwordx4 v[106:109], v[118:119], off offset:192
	v_mfma_f32_16x16x32_bf16 v[90:93], v[36:39], v[154:157], v[138:141]
	s_waitcnt vmcnt(0)
	v_pk_mul_f32 v[24:25], v[24:25], s[22:23] op_sel_hi:[1,0]
	v_mfma_f32_16x16x32_bf16 v[102:105], v[32:35], v[154:157], v[142:145]
	v_mul_f32_e64 v26, v26, s22
	v_mul_f32_e64 v27, v27, s22
	v_pk_mul_f32 v[94:95], v[94:95], s[22:23] op_sel_hi:[1,0]
	v_pk_mul_f32 v[96:97], v[96:97], s[22:23] op_sel_hi:[1,0]
	v_pk_mul_f32 v[98:99], v[98:99], s[22:23] op_sel_hi:[1,0]
	v_pk_mul_f32 v[100:101], v[100:101], s[22:23] op_sel_hi:[1,0]
	v_pk_mul_f32 v[106:107], v[106:107], s[22:23] op_sel_hi:[1,0]
	v_pk_mul_f32 v[108:109], v[108:109], s[22:23] op_sel_hi:[1,0]
	v_pk_fma_f32 v[24:25], v[114:115], v[16:17], v[24:25]
	v_pk_fma_f32 v[26:27], v[116:117], v[18:19], v[26:27]
	v_pk_fma_f32 v[94:95], v[122:123], v[0:1], v[94:95]
	v_pk_fma_f32 v[96:97], v[124:125], v[2:3], v[96:97]
	v_pk_fma_f32 v[90:91], v[90:91], v[8:9], v[98:99]
	v_pk_fma_f32 v[92:93], v[92:93], v[10:11], v[100:101]
	v_pk_fma_f32 v[98:99], v[102:103], v[12:13], v[106:107]
	v_pk_fma_f32 v[100:101], v[104:105], v[14:15], v[108:109]
	global_store_dwordx4 v[118:119], v[24:27], off
	global_store_dwordx4 v[118:119], v[94:97], off offset:64
	global_store_dwordx4 v[118:119], v[90:93], off offset:128
	global_store_dwordx4 v[118:119], v[98:101], off offset:192
	v_mfma_f32_16x16x32_bf16 v[110:113], v[44:47], v[56:59], v[146:149]
	v_ashrrev_i32_e32 v165, 31, v164
	v_lshlrev_b64 v[24:25], 12, v[164:165]
	v_lshl_add_u64 v[24:25], s[52:53], 0, v[24:25]
	v_lshl_add_u64 v[24:25], v[24:25], 0, v[78:79]
	v_lshl_add_u64 v[106:107], v[24:25], 0, v[76:77]
	global_load_dwordx4 v[24:27], v[106:107], off
	global_load_dwordx4 v[94:97], v[106:107], off offset:64
	global_load_dwordx4 v[98:101], v[106:107], off offset:128
	global_load_dwordx4 v[102:105], v[106:107], off offset:192
	v_mfma_f32_16x16x32_bf16 v[90:93], v[40:43], v[56:59], v[158:161]
	s_waitcnt vmcnt(0)
	v_pk_mul_f32 v[24:25], v[24:25], s[22:23] op_sel_hi:[1,0]
	v_mfma_f32_16x16x32_bf16 v[64:67], v[36:39], v[56:59], v[64:67]
	v_mul_f32_e64 v26, v26, s22
	v_mul_f32_e64 v27, v27, s22
	v_pk_fma_f32 v[24:25], v[110:111], v[16:17], v[24:25]
	v_pk_fma_f32 v[26:27], v[112:113], v[18:19], v[26:27]
	v_mfma_f32_16x16x32_bf16 v[56:59], v[32:35], v[56:59], v[60:63]
	s_nop 2
	v_mul_f32_e64 v60, v94, s22
	v_mul_f32_e64 v61, v95, s22
	v_pk_mul_f32 v[62:63], v[96:97], s[22:23] op_sel_hi:[1,0]
	v_pk_mul_f32 v[94:95], v[98:99], s[22:23] op_sel_hi:[1,0]
	v_pk_mul_f32 v[96:97], v[100:101], s[22:23] op_sel_hi:[1,0]
	v_pk_mul_f32 v[98:99], v[102:103], s[22:23] op_sel_hi:[1,0]
	v_pk_mul_f32 v[100:101], v[104:105], s[22:23] op_sel_hi:[1,0]
	v_pk_fma_f32 v[60:61], v[90:91], v[0:1], v[60:61]
	v_pk_fma_f32 v[62:63], v[92:93], v[2:3], v[62:63]
	v_pk_fma_f32 v[64:65], v[64:65], v[8:9], v[94:95]
	v_pk_fma_f32 v[66:67], v[66:67], v[10:11], v[96:97]
	v_pk_fma_f32 v[56:57], v[56:57], v[12:13], v[98:99]
	v_pk_fma_f32 v[58:59], v[58:59], v[14:15], v[100:101]
	global_store_dwordx4 v[106:107], v[24:27], off
	global_store_dwordx4 v[106:107], v[60:63], off offset:64
	global_store_dwordx4 v[106:107], v[64:67], off offset:128
	global_store_dwordx4 v[106:107], v[56:59], off offset:192
	v_mfma_f32_16x16x32_bf16 v[44:47], v[44:47], v[28:31], v[52:55]
	v_ashrrev_i32_e32 v81, 31, v80
	v_lshlrev_b64 v[24:25], 12, v[80:81]
	v_lshl_add_u64 v[24:25], s[52:53], 0, v[24:25]
	v_lshl_add_u64 v[24:25], v[24:25], 0, v[78:79]
	v_lshl_add_u64 v[60:61], v[24:25], 0, v[76:77]
	global_load_dwordx4 v[24:27], v[60:61], off
	global_load_dwordx4 v[52:55], v[60:61], off offset:64
	global_load_dwordx4 v[56:59], v[60:61], off offset:128
	v_mfma_f32_16x16x32_bf16 v[40:43], v[40:43], v[28:31], v[48:51]
	s_waitcnt vmcnt(0)
	v_pk_mul_f32 v[24:25], v[24:25], s[22:23] op_sel_hi:[1,0]
	s_nop 0
	global_load_dwordx4 v[48:51], v[60:61], off offset:192
	v_mfma_f32_16x16x32_bf16 v[20:23], v[36:39], v[28:31], v[20:23]
	v_mul_f32_e64 v26, v26, s22
	v_mul_f32_e64 v27, v27, s22
	v_pk_fma_f32 v[16:17], v[44:45], v[16:17], v[24:25]
	v_pk_fma_f32 v[18:19], v[46:47], v[18:19], v[26:27]
	v_mfma_f32_16x16x32_bf16 v[4:7], v[32:35], v[28:31], v[4:7]
	v_mul_f32_e64 v28, v52, s22
	v_mul_f32_e64 v29, v53, s22
	v_pk_mul_f32 v[30:31], v[54:55], s[22:23] op_sel_hi:[1,0]
	v_pk_mul_f32 v[32:33], v[56:57], s[22:23] op_sel_hi:[1,0]
	v_pk_mul_f32 v[34:35], v[58:59], s[22:23] op_sel_hi:[1,0]
	v_pk_fma_f32 v[0:1], v[40:41], v[0:1], v[28:29]
	v_pk_fma_f32 v[2:3], v[42:43], v[2:3], v[30:31]
	v_pk_fma_f32 v[8:9], v[20:21], v[8:9], v[32:33]
	v_pk_fma_f32 v[10:11], v[22:23], v[10:11], v[34:35]
	s_waitcnt vmcnt(0)
	v_pk_mul_f32 v[36:37], v[48:49], s[22:23] op_sel_hi:[1,0]
	v_pk_mul_f32 v[38:39], v[50:51], s[22:23] op_sel_hi:[1,0]
	v_pk_fma_f32 v[4:5], v[4:5], v[12:13], v[36:37]
	v_pk_fma_f32 v[6:7], v[6:7], v[14:15], v[38:39]
	global_store_dwordx4 v[60:61], v[16:19], off
	global_store_dwordx4 v[60:61], v[0:3], off offset:64
	global_store_dwordx4 v[60:61], v[8:11], off offset:128
	global_store_dwordx4 v[60:61], v[4:7], off offset:192
	s_cbranch_scc0 .LBB0_2891

.LBB0_3063:
	s_lshl_b32 s41, s39, 14
	s_waitcnt vmcnt(0)
	v_lshl_add_u64 v[116:117], v[74:75], 0, s[18:19]
	s_add_i32 s41, s21, s41
	s_waitcnt lgkmcnt(0)
	s_barrier
	v_lshl_add_u64 v[84:85], v[116:117], 0, s[6:7]
	s_mov_b32 m0, s41
	v_lshl_add_u64 v[118:119], v[72:73], 0, s[18:19]
	v_lshl_add_u64 v[86:87], v[116:117], 0, s[8:9]
	global_load_lds_dwordx4 v[84:85], off
	s_add_i32 m0, s41, 0x400
	v_lshl_add_u64 v[88:89], v[118:119], 0, s[6:7]
	global_load_lds_dwordx4 v[86:87], off
	s_add_i32 m0, s41, 0x2000
	s_lshl_b32 s42, s40, 14
	global_load_lds_dwordx4 v[88:89], off
	s_add_i32 m0, s41, 0x2400
	s_add_i32 s41, s40, 1
	s_cmp_lg_u32 s40, 3
	s_cselect_b32 s40, s41, 0
	s_add_i32 s41, s39, 1
	v_lshl_add_u64 v[90:91], v[118:119], 0, s[8:9]
	s_cmp_lg_u32 s39, 3
	global_load_lds_dwordx4 v[90:91], off
	s_cselect_b32 s39, s41, 0
	v_add_u32_e32 v120, s42, v80
	v_or_b32_e32 v121, s42, v81
	ds_read_b128 v[84:87], v120
	ds_read_b128 v[88:91], v120 offset:1024
	ds_read_b128 v[92:95], v120 offset:2048
	ds_read_b128 v[96:99], v120 offset:3072
	ds_read_b128 v[100:103], v121
	ds_read_b128 v[104:107], v121 offset:1024
	ds_read_b128 v[108:111], v121 offset:2048
	ds_read_b128 v[112:115], v121 offset:3072
	s_lshl_b32 s98, s40, 14
	v_add_u32_e32 v194, s98, v80
	v_or_b32_e32 v195, s98, v81
	ds_read_b128 v[162:165], v194
	ds_read_b128 v[166:169], v194 offset:1024
	ds_read_b128 v[170:173], v194 offset:2048
	ds_read_b128 v[174:177], v194 offset:3072
	ds_read_b128 v[178:181], v195
	ds_read_b128 v[182:185], v195 offset:1024
	ds_read_b128 v[186:189], v195 offset:2048
	ds_read_b128 v[190:193], v195 offset:3072
	s_waitcnt lgkmcnt(8)
	s_lshl_b32 s41, s39, 14
	s_add_i32 s41, s21, s41
	v_mfma_f32_16x16x32_bf16 v[60:63], v[100:103], v[84:87], v[60:63]
	v_mfma_f32_16x16x32_bf16 v[56:59], v[104:107], v[84:87], v[56:59]
	s_mov_b32 m0, s41
	v_mfma_f32_16x16x32_bf16 v[52:55], v[108:111], v[84:87], v[52:55]
	v_mfma_f32_16x16x32_bf16 v[48:51], v[112:115], v[84:87], v[48:51]
	v_lshl_add_u64 v[84:85], v[116:117], 0, s[10:11]
	v_lshl_add_u64 v[86:87], v[116:117], 0, s[12:13]
	global_load_lds_dwordx4 v[84:85], off
	s_add_i32 m0, s41, 0x400
	v_mfma_f32_16x16x32_bf16 v[44:47], v[100:103], v[88:91], v[44:47]
	global_load_lds_dwordx4 v[86:87], off
	s_add_i32 m0, s41, 0x2000
	v_mfma_f32_16x16x32_bf16 v[40:43], v[104:107], v[88:91], v[40:43]
	v_mfma_f32_16x16x32_bf16 v[36:39], v[108:111], v[88:91], v[36:39]
	v_mfma_f32_16x16x32_bf16 v[32:35], v[112:115], v[88:91], v[32:35]
	v_lshl_add_u64 v[88:89], v[118:119], 0, s[10:11]
	v_lshl_add_u64 v[90:91], v[118:119], 0, s[12:13]
	global_load_lds_dwordx4 v[88:89], off
	s_add_i32 m0, s41, 0x2400
	v_mfma_f32_16x16x32_bf16 v[28:31], v[100:103], v[92:95], v[28:31]
	global_load_lds_dwordx4 v[90:91], off
	s_lshl_b32 s41, s40, 14
	v_mfma_f32_16x16x32_bf16 v[24:27], v[104:107], v[92:95], v[24:27]
	v_add_u32_e32 v116, s41, v80
	v_or_b32_e32 v117, s41, v81
	s_add_i32 s41, s40, 1
	v_mfma_f32_16x16x32_bf16 v[16:19], v[108:111], v[92:95], v[16:19]
	s_cmp_lg_u32 s40, 3
	s_cselect_b32 s40, s41, 0
	s_add_i32 s41, s39, 1
	v_mfma_f32_16x16x32_bf16 v[12:15], v[112:115], v[92:95], v[12:15]
	s_cmp_lg_u32 s39, 3
	s_cselect_b32 s39, s41, 0
	s_add_u32 s18, s18, 0x80
	v_mfma_f32_16x16x32_bf16 v[8:11], v[100:103], v[96:99], v[8:11]
	s_addc_u32 s19, s19, 0
	s_cmpk_eq_i32 s18, 0x1580
	v_mfma_f32_16x16x32_bf16 v[4:7], v[104:107], v[96:99], v[4:7]
	v_mfma_f32_16x16x32_bf16 v[0:3], v[108:111], v[96:99], v[0:3]
	v_mfma_f32_16x16x32_bf16 v[20:23], v[112:115], v[96:99], v[20:23]
	s_waitcnt lgkmcnt(0)
	s_nop 0
	v_mfma_f32_16x16x32_bf16 v[60:63], v[178:181], v[162:165], v[60:63]
	v_mfma_f32_16x16x32_bf16 v[56:59], v[182:185], v[162:165], v[56:59]
	v_mfma_f32_16x16x32_bf16 v[52:55], v[186:189], v[162:165], v[52:55]
	v_mfma_f32_16x16x32_bf16 v[48:51], v[190:193], v[162:165], v[48:51]
	v_mfma_f32_16x16x32_bf16 v[44:47], v[178:181], v[166:169], v[44:47]
	v_mfma_f32_16x16x32_bf16 v[40:43], v[182:185], v[166:169], v[40:43]
	v_mfma_f32_16x16x32_bf16 v[36:39], v[186:189], v[166:169], v[36:39]
	v_mfma_f32_16x16x32_bf16 v[32:35], v[190:193], v[166:169], v[32:35]
	v_mfma_f32_16x16x32_bf16 v[28:31], v[178:181], v[170:173], v[28:31]
	v_mfma_f32_16x16x32_bf16 v[24:27], v[182:185], v[170:173], v[24:27]
	v_mfma_f32_16x16x32_bf16 v[16:19], v[186:189], v[170:173], v[16:19]
	v_mfma_f32_16x16x32_bf16 v[12:15], v[190:193], v[170:173], v[12:15]
	v_mfma_f32_16x16x32_bf16 v[8:11], v[178:181], v[174:177], v[8:11]
	v_mfma_f32_16x16x32_bf16 v[4:7], v[182:185], v[174:177], v[4:7]
	v_mfma_f32_16x16x32_bf16 v[0:3], v[186:189], v[174:177], v[0:3]
	v_mfma_f32_16x16x32_bf16 v[20:23], v[190:193], v[174:177], v[20:23]
	s_cbranch_scc0 .LBB0_3063
	s_waitcnt vmcnt(4)
	s_waitcnt lgkmcnt(0)
	s_barrier
	ds_read_b128 v[72:75], v80 offset:32768
	ds_read_b128 v[84:87], v80 offset:33792
	ds_read_b128 v[88:91], v80 offset:34816
	ds_read_b128 v[92:95], v80 offset:35840
	ds_read_b128 v[96:99], v81 offset:32768
	ds_read_b128 v[100:103], v81 offset:33792
	ds_read_b128 v[104:107], v81 offset:34816
	ds_read_b128 v[108:111], v81 offset:35840
	s_waitcnt lgkmcnt(0)
	s_waitcnt vmcnt(0)
	s_waitcnt lgkmcnt(0)
	s_barrier
	v_mfma_f32_16x16x32_bf16 v[112:115], v[96:99], v[72:75], v[60:63]
	v_readlane_b32 s40, v241, 1
	v_readlane_b32 s48, v241, 9
	v_mfma_f32_16x16x32_bf16 v[116:119], v[100:103], v[72:75], v[56:59]
	v_readlane_b32 s49, v241, 10
	s_add_i32 s2, s2, s3
	s_add_i32 s22, s22, s23
	v_mfma_f32_16x16x32_bf16 v[120:123], v[104:107], v[72:75], v[52:55]
	v_readlane_b32 s41, v241, 2
	v_readlane_b32 s42, v241, 3
	v_readlane_b32 s43, v241, 4
	v_mfma_f32_16x16x32_bf16 v[124:127], v[108:111], v[72:75], v[48:51]
	v_add_u32_e32 v74, s37, v78
	v_cmp_lt_i32_e32 vcc, s35, v74
	v_readlane_b32 s44, v241, 5
	v_mfma_f32_16x16x32_bf16 v[60:63], v[104:107], v[88:91], v[16:19]
	v_readlane_b32 s45, v241, 6
	v_readlane_b32 s46, v241, 7
	v_readlane_b32 s47, v241, 8
	v_add_u32_e32 v16, 0xfffff000, v74
	v_lshrrev_b32_e32 v16, 12, v16
	v_mfma_f32_16x16x32_bf16 v[152:155], v[100:103], v[88:91], v[24:27]
	v_add_u32_e32 v16, 6, v16
	v_readlane_b32 s50, v241, 11
	v_readlane_b32 s51, v241, 12
	v_or_b32_e32 v24, s38, v79
	v_mfma_f32_16x16x32_bf16 v[56:59], v[108:111], v[88:91], v[12:15]
	v_ashrrev_i32_e32 v25, 31, v24
	v_lshlrev_b64 v[72:73], 2, v[24:25]
	v_readlane_b32 s52, v241, 13
	v_cndmask_b32_e32 v12, 5, v16, vcc
	v_mad_u64_u32 v[12:13], s[18:19], v12, s30, v[70:71]
	v_mfma_f32_16x16x32_bf16 v[48:51], v[96:99], v[92:95], v[8:11]
	v_readlane_b32 s53, v241, 14
	v_readlane_b32 s54, v241, 15
	v_readlane_b32 s55, v241, 16
	v_lshl_add_u64 v[8:9], v[12:13], 0, v[72:73]
	v_lshl_add_u64 v[12:13], v[8:9], 0, v[64:65]
	v_mfma_f32_16x16x32_bf16 v[128:131], v[96:99], v[84:87], v[44:47]
	v_add_co_u32_e32 v18, vcc, s36, v12
	v_lshl_add_u64 v[16:17], v[12:13], 0, s[14:15]
	v_mfma_f32_16x16x32_bf16 v[132:135], v[100:103], v[84:87], v[40:43]
	v_addc_co_u32_e32 v19, vcc, 0, v13, vcc
	v_mfma_f32_16x16x32_bf16 v[136:139], v[104:107], v[84:87], v[36:39]
	v_mfma_f32_16x16x32_bf16 v[84:87], v[108:111], v[84:87], v[32:35]
	v_mfma_f32_16x16x32_bf16 v[140:143], v[96:99], v[88:91], v[28:31]
	ds_read_b128 v[144:147], v80 offset:49152
	ds_read_b128 v[148:151], v80 offset:50176
	ds_read_b128 v[52:55], v80 offset:51200
	ds_read_b128 v[28:31], v80 offset:52224
	ds_read_b128 v[44:47], v81 offset:49152
	ds_read_b128 v[40:43], v81 offset:50176
	ds_read_b128 v[36:39], v81 offset:51200
	ds_read_b128 v[32:35], v81 offset:52224
	s_waitcnt lgkmcnt(0)
	s_waitcnt lgkmcnt(0)
	s_barrier
	v_or_b32_e32 v96, v74, v76
	v_mfma_f32_16x16x32_bf16 v[24:27], v[100:103], v[92:95], v[4:7]
	v_or_b32_e32 v156, 16, v96
	v_or_b32_e32 v158, 32, v96
	v_or_b32_e32 v74, 48, v96
	v_mfma_f32_16x16x32_bf16 v[4:7], v[104:107], v[92:95], v[0:3]
	s_nop 2
	global_load_dwordx4 v[0:3], v[16:17], off offset:64
	global_load_dwordx4 v[12:15], v[16:17], off offset:128
	v_mfma_f32_16x16x32_bf16 v[8:11], v[108:111], v[92:95], v[20:23]
	s_nop 2
	global_load_dwordx4 v[20:23], v[18:19], off
	s_nop 0
	global_load_dwordx4 v[16:19], v[16:17], off offset:192
	s_nop 0
	v_ashrrev_i32_e32 v97, 31, v96
	v_lshlrev_b64 v[96:97], 12, v[96:97]
	v_lshl_add_u64 v[100:101], s[48:49], 0, v[96:97]
	v_lshl_add_u64 v[100:101], v[100:101], 0, v[72:73]
	v_lshl_add_u64 v[160:161], v[100:101], 0, v[64:65]
	global_load_dwordx4 v[100:103], v[160:161], off
	v_mfma_f32_16x16x32_bf16 v[88:91], v[44:47], v[144:147], v[112:115]
	global_load_dwordx4 v[108:111], v[160:161], off offset:64
	s_nop 1
	global_load_dwordx4 v[112:115], v[160:161], off offset:128
	s_waitcnt vmcnt(0)
	v_pk_mul_f32 v[100:101], v[100:101], s[16:17] op_sel_hi:[1,0]
	v_mfma_f32_16x16x32_bf16 v[96:99], v[36:39], v[144:147], v[120:123]
	v_mul_f32_e64 v102, v102, s16
	v_mul_f32_e64 v103, v103, s16
	v_pk_mul_f32 v[108:109], v[108:109], s[16:17] op_sel_hi:[1,0]
	v_pk_mul_f32 v[110:111], v[110:111], s[16:17] op_sel_hi:[1,0]
	global_load_dwordx4 v[120:123], v[160:161], off offset:192
	v_mfma_f32_16x16x32_bf16 v[92:95], v[40:43], v[144:147], v[116:119]
	v_mul_f32_e64 v112, v112, s16
	v_mul_f32_e64 v113, v113, s16
	v_pk_mul_f32 v[114:115], v[114:115], s[16:17] op_sel_hi:[1,0]
	v_pk_fma_f32 v[88:89], v[88:89], v[20:21], v[100:101]
	v_mfma_f32_16x16x32_bf16 v[104:107], v[32:35], v[144:147], v[124:127]
	v_fma_f32 v90, v90, v22, v102
	v_fma_f32 v91, v91, v23, v103
	s_nop 0
	v_pk_fma_f32 v[92:93], v[92:93], v[0:1], v[108:109]
	v_pk_fma_f32 v[94:95], v[94:95], v[2:3], v[110:111]
	v_pk_fma_f32 v[96:97], v[96:97], v[12:13], v[112:113]
	v_pk_fma_f32 v[98:99], v[98:99], v[14:15], v[114:115]
	v_mfma_f32_16x16x32_bf16 v[116:119], v[44:47], v[148:151], v[128:131]
	s_waitcnt vmcnt(0)
	v_pk_mul_f32 v[120:121], v[120:121], s[16:17] op_sel_hi:[1,0]
	v_pk_mul_f32 v[122:123], v[122:123], s[16:17] op_sel_hi:[1,0]
	v_pk_fma_f32 v[100:101], v[104:105], v[16:17], v[120:121]
	v_pk_fma_f32 v[102:103], v[106:107], v[18:19], v[122:123]
	global_store_dwordx4 v[160:161], v[88:91], off
	global_store_dwordx4 v[160:161], v[92:95], off offset:64
	global_store_dwordx4 v[160:161], v[96:99], off offset:128
	global_store_dwordx4 v[160:161], v[100:103], off offset:192
	v_mfma_f32_16x16x32_bf16 v[124:127], v[40:43], v[148:151], v[132:135]
	v_ashrrev_i32_e32 v157, 31, v156
	v_lshlrev_b64 v[88:89], 12, v[156:157]
	v_lshl_add_u64 v[88:89], s[48:49], 0, v[88:89]
	v_lshl_add_u64 v[88:89], v[88:89], 0, v[72:73]
	v_lshl_add_u64 v[112:113], v[88:89], 0, v[64:65]
	global_load_dwordx4 v[88:91], v[112:113], off
	global_load_dwordx4 v[96:99], v[112:113], off offset:64
	global_load_dwordx4 v[100:103], v[112:113], off offset:128
	global_load_dwordx4 v[104:107], v[112:113], off offset:192
	v_mfma_f32_16x16x32_bf16 v[92:95], v[36:39], v[148:151], v[136:139]
	s_waitcnt vmcnt(0)
	v_pk_mul_f32 v[88:89], v[88:89], s[16:17] op_sel_hi:[1,0]
	v_mfma_f32_16x16x32_bf16 v[84:87], v[32:35], v[148:151], v[84:87]
	v_mul_f32_e64 v90, v90, s16
	v_mul_f32_e64 v91, v91, s16
	v_pk_mul_f32 v[96:97], v[96:97], s[16:17] op_sel_hi:[1,0]
	v_pk_mul_f32 v[98:99], v[98:99], s[16:17] op_sel_hi:[1,0]
	v_pk_mul_f32 v[100:101], v[100:101], s[16:17] op_sel_hi:[1,0]
	v_pk_mul_f32 v[102:103], v[102:103], s[16:17] op_sel_hi:[1,0]
	v_pk_mul_f32 v[104:105], v[104:105], s[16:17] op_sel_hi:[1,0]
	v_pk_mul_f32 v[106:107], v[106:107], s[16:17] op_sel_hi:[1,0]
	v_pk_fma_f32 v[88:89], v[116:117], v[20:21], v[88:89]
	v_pk_fma_f32 v[90:91], v[118:119], v[22:23], v[90:91]
	v_pk_fma_f32 v[96:97], v[124:125], v[0:1], v[96:97]
	v_pk_fma_f32 v[98:99], v[126:127], v[2:3], v[98:99]
	v_pk_fma_f32 v[92:93], v[92:93], v[12:13], v[100:101]
	v_pk_fma_f32 v[94:95], v[94:95], v[14:15], v[102:103]
	v_pk_fma_f32 v[84:85], v[84:85], v[16:17], v[104:105]
	v_pk_fma_f32 v[86:87], v[86:87], v[18:19], v[106:107]
	global_store_dwordx4 v[112:113], v[88:91], off
	global_store_dwordx4 v[112:113], v[96:99], off offset:64
	global_store_dwordx4 v[112:113], v[92:95], off offset:128
	global_store_dwordx4 v[112:113], v[84:87], off offset:192
	v_mfma_f32_16x16x32_bf16 v[108:111], v[44:47], v[52:55], v[140:143]
	v_ashrrev_i32_e32 v159, 31, v158
	v_lshlrev_b64 v[84:85], 12, v[158:159]
	v_lshl_add_u64 v[84:85], s[48:49], 0, v[84:85]
	v_lshl_add_u64 v[84:85], v[84:85], 0, v[72:73]
	v_lshl_add_u64 v[104:105], v[84:85], 0, v[64:65]
	global_load_dwordx4 v[84:87], v[104:105], off
	global_load_dwordx4 v[92:95], v[104:105], off offset:64
	global_load_dwordx4 v[96:99], v[104:105], off offset:128
	global_load_dwordx4 v[100:103], v[104:105], off offset:192
	v_mfma_f32_16x16x32_bf16 v[88:91], v[40:43], v[52:55], v[152:155]
	v_mfma_f32_16x16x32_bf16 v[60:63], v[36:39], v[52:55], v[60:63]
	v_mfma_f32_16x16x32_bf16 v[52:55], v[32:35], v[52:55], v[56:59]
	v_mfma_f32_16x16x32_bf16 v[44:47], v[44:47], v[28:31], v[48:51]
	s_waitcnt vmcnt(0)
	s_nop 0
	v_pk_mul_f32 v[56:57], v[84:85], s[16:17] op_sel_hi:[1,0]
	v_pk_mul_f32 v[58:59], v[86:87], s[16:17] op_sel_hi:[1,0]
	v_pk_mul_f32 v[84:85], v[92:93], s[16:17] op_sel_hi:[1,0]
	v_pk_mul_f32 v[86:87], v[94:95], s[16:17] op_sel_hi:[1,0]
	v_pk_mul_f32 v[92:93], v[96:97], s[16:17] op_sel_hi:[1,0]
	v_pk_mul_f32 v[94:95], v[98:99], s[16:17] op_sel_hi:[1,0]
	v_pk_mul_f32 v[96:97], v[100:101], s[16:17] op_sel_hi:[1,0]
	v_pk_mul_f32 v[98:99], v[102:103], s[16:17] op_sel_hi:[1,0]
	v_pk_fma_f32 v[56:57], v[108:109], v[20:21], v[56:57]
	v_pk_fma_f32 v[58:59], v[110:111], v[22:23], v[58:59]
	v_pk_fma_f32 v[84:85], v[88:89], v[0:1], v[84:85]
	v_pk_fma_f32 v[86:87], v[90:91], v[2:3], v[86:87]
	v_pk_fma_f32 v[60:61], v[60:61], v[12:13], v[92:93]
	v_pk_fma_f32 v[62:63], v[62:63], v[14:15], v[94:95]
	v_pk_fma_f32 v[52:53], v[52:53], v[16:17], v[96:97]
	v_pk_fma_f32 v[54:55], v[54:55], v[18:19], v[98:99]
	global_store_dwordx4 v[104:105], v[56:59], off
	global_store_dwordx4 v[104:105], v[84:87], off offset:64
	global_store_dwordx4 v[104:105], v[60:63], off offset:128
	global_store_dwordx4 v[104:105], v[52:55], off offset:192
	v_mfma_f32_16x16x32_bf16 v[24:27], v[40:43], v[28:31], v[24:27]
	v_ashrrev_i32_e32 v75, 31, v74
	v_lshlrev_b64 v[52:53], 12, v[74:75]
	v_lshl_add_u64 v[52:53], s[48:49], 0, v[52:53]
	v_lshl_add_u64 v[52:53], v[52:53], 0, v[72:73]
	v_lshl_add_u64 v[60:61], v[52:53], 0, v[64:65]
	global_load_dwordx4 v[52:55], v[60:61], off
	global_load_dwordx4 v[48:51], v[60:61], off offset:64
	global_load_dwordx4 v[56:59], v[60:61], off offset:128
	global_load_dwordx4 v[40:43], v[60:61], off offset:192
	v_mfma_f32_16x16x32_bf16 v[4:7], v[36:39], v[28:31], v[4:7]
	s_add_i32 s17, s17, s34
	s_cmpk_gt_i32 s2, 0x9f
	s_waitcnt vmcnt(0)
	v_pk_mul_f32 v[36:37], v[56:57], s[16:17] op_sel_hi:[1,0]
	v_mfma_f32_16x16x32_bf16 v[8:11], v[32:35], v[28:31], v[8:11]
	v_mul_f32_e64 v28, v52, s16
	v_mul_f32_e64 v29, v53, s16
	v_pk_mul_f32 v[30:31], v[54:55], s[16:17] op_sel_hi:[1,0]
	v_pk_mul_f32 v[32:33], v[48:49], s[16:17] op_sel_hi:[1,0]
	v_pk_mul_f32 v[34:35], v[50:51], s[16:17] op_sel_hi:[1,0]
	v_pk_mul_f32 v[38:39], v[58:59], s[16:17] op_sel_hi:[1,0]
	v_pk_mul_f32 v[40:41], v[40:41], s[16:17] op_sel_hi:[1,0]
	v_pk_mul_f32 v[42:43], v[42:43], s[16:17] op_sel_hi:[1,0]
	v_pk_fma_f32 v[20:21], v[44:45], v[20:21], v[28:29]
	v_pk_fma_f32 v[22:23], v[46:47], v[22:23], v[30:31]
	v_pk_fma_f32 v[0:1], v[24:25], v[0:1], v[32:33]
	v_pk_fma_f32 v[2:3], v[26:27], v[2:3], v[34:35]
	v_pk_fma_f32 v[4:5], v[4:5], v[12:13], v[36:37]
	v_pk_fma_f32 v[6:7], v[6:7], v[14:15], v[38:39]
	v_pk_fma_f32 v[8:9], v[8:9], v[16:17], v[40:41]
	v_pk_fma_f32 v[10:11], v[10:11], v[18:19], v[42:43]
	global_store_dwordx4 v[60:61], v[20:23], off
	global_store_dwordx4 v[60:61], v[0:3], off offset:64
	global_store_dwordx4 v[60:61], v[4:7], off offset:128
	global_store_dwordx4 v[60:61], v[8:11], off offset:192
	s_cbranch_scc0 .LBB0_3062
